# GEMM K-loop: k=1 A-fragment LDS reads of the 12-read phases deferred into MFMA shadows (lgkmcnt(8)->(4)); setprio flips moved across barriers; tail ALU in MFMA gaps
# speedup vs baseline: 1.0312x; 1.0053x over previous
; #define PG8_STAGE(bufoff, gbase, voff) do { _Pragma("unroll") for (int _i = 0; _i < 2; ++_i) \
;         __builtin_amdgcn_global_load_lds((const unsigned*)((const char*)(gbase) + (voff)[_i]), (LAS unsigned*)(lds + (bufoff) + ldsw + _i * 8192), 16, 0, 0); } while (0)
; #define PG8_LDA(dst, b, h) do { _Pragma("unroll") for (int m = 0; m < 4; ++m) _Pragma("unroll") for (int k = 0; k < 2; ++k) dst[m][k] = *(const LAS bf16x8*)(lds + PG8_SA(b, h) + aoff + m * 2048 + k * 1024); } while (0)
; #define PG8_LDB(dst, b, h) do { _Pragma("unroll") for (int n = 0; n < 2; ++n) _Pragma("unroll") for (int k = 0; k < 2; ++k) dst[n][k] = *(const LAS bf16x8*)(lds + PG8_SB(b, h) + boff + n * 2048 + k * 1024); } while (0)
; #define PG8_MMA(ai, bj, At, Bt) do { __builtin_amdgcn_s_setprio(1); _Pragma("unroll") for (int m = 0; m < 4; ++m) _Pragma("unroll") for (int n = 0; n < 2; ++n) _Pragma("unroll") for (int k = 0; k < 2; ++k) \
;         acc[ai][bj][m][n] = __builtin_amdgcn_mfma_f32_16x16x32_bf16(Bt[n][k], At[m][k], acc[ai][bj][m][n], 0, 0, 0); __builtin_amdgcn_s_setprio(0); } while (0)
; #define PG8_BAR __builtin_amdgcn_s_barrier()
; template <class Epi, class Sched>
; __device__ __forceinline__ void gemm_phase(LAS unsigned char* lds, const Gemm g, const Sched& S, const Epi& E, int tid) {
;     ...
;     for (;;) {
;         const bool has_next = S.next(ui + 1, nxt);
;         const char* nA = has_next ? (const char*)g.A + (size_t)nxt.pm * tstep : cA; const char* nB = has_next ? (const char*)g.Bt + (size_t)nxt.pn * tstep : cB;
;         for (int t = 0; t < nt; t += 2) {
;             const bool last = (t == nt - 2);
;             const char* a1 = cA + (size_t)(t + 1) * kstep;
;             const char* a2 = last ? nA : cA + (size_t)(t + 2) * kstep; const char* b2 = last ? nB : cB + (size_t)(t + 2) * kstep;
;             const char* a3 = a2 + kstep; const char* b3 = b2 + kstep;
;             PG8_LDB(B0, 0, 0); PG8_SCHED; PG8_LDA(At, 0, 0); PG8_STAGE(PG8_SA(1, 1), a1 + hstep, voffA);
;             PG8_WAIT_L(8); PG8_BAR; PG8_WAIT_L(0); PG8_MMA(0, 0, At, B0); PG8_BAR; PG8_SCHED;
;             PG8_LDB(B1, 0, 1); PG8_STAGE(PG8_SB(0, 0), b2, voffB);
;             PG8_BAR; PG8_WAIT_L(0); PG8_MMA(0, 1, At, B1); PG8_BAR;
;             PG8_LDA(At, 0, 1); PG8_STAGE(PG8_SA(0, 0), a2, voffA);
;             PG8_BAR; PG8_WAIT_L(0); PG8_MMA(1, 0, At, B0); PG8_BAR; PG8_SCHED;
.LBB0_99:
	s_add_u32 vcc_lo, s44, 0x80
	s_addc_u32 vcc_hi, s45, 0
	s_add_u32 s96, s34, 0x100
	s_addc_u32 s65, s35, 0
	s_mov_b32 s34, 0
	s_add_i32 s0, s34, 2
	s_add_u32 s1, vcc_lo, 0x80
	s_addc_u32 s35, vcc_hi, 0
	s_add_i32 s17, 0, 0x10000
	v_add_u32_e32 v152, s17, v141
	ds_read_b128 v[144:147], v152
	ds_read_b128 v[148:151], v152 offset:1024
	ds_read_b128 v[160:163], v152 offset:2048
	ds_read_b128 v[164:167], v152 offset:3072
	s_cmp_eq_u32 s95, s34
	s_cselect_b32 s34, s38, s1
	s_cselect_b32 s35, s39, s35
	s_cselect_b32 s45, s41, s65
	s_cselect_b32 s44, s40, s96
	v_lshl_add_u64 v[152:153], vcc, 0, v[134:135]
	s_add_i32 m0, s88, 0xc000
	ds_read_b128 v[168:171], v143
	ds_read_b128 v[188:191], v143 offset:2048
	ds_read_b128 v[196:199], v143 offset:4096
	ds_read_b128 v[204:207], v143 offset:6144
	global_load_lds_dwordx4 v[152:153], off
	v_lshl_add_u64 v[152:153], vcc, 0, v[136:137]
	s_add_i32 m0, s88, 0xe000
	s_nop 0
	global_load_lds_dwordx4 v[152:153], off
	s_waitcnt lgkmcnt(4)
	s_setprio 1
	s_barrier
	s_waitcnt lgkmcnt(0)
	v_mfma_f32_16x16x32_bf16 v[124:127], v[144:147], v[168:171], 0
	ds_read_b128 v[184:187], v143 offset:1024
	v_mfma_f32_16x16x32_bf16 v[120:123], v[160:163], v[168:171], 0
	ds_read_b128 v[192:195], v143 offset:3072
	v_mfma_f32_16x16x32_bf16 v[116:119], v[144:147], v[188:191], 0
	ds_read_b128 v[200:203], v143 offset:5120
	v_mfma_f32_16x16x32_bf16 v[112:115], v[160:163], v[188:191], 0
	ds_read_b128 v[208:211], v143 offset:7168
	v_mfma_f32_16x16x32_bf16 v[100:103], v[144:147], v[196:199], 0
	v_mfma_f32_16x16x32_bf16 v[96:99], v[160:163], v[196:199], 0
	v_mfma_f32_16x16x32_bf16 v[84:87], v[144:147], v[204:207], 0
	v_mfma_f32_16x16x32_bf16 v[80:83], v[160:163], v[204:207], 0
	s_waitcnt lgkmcnt(0)
	v_mfma_f32_16x16x32_bf16 v[124:127], v[148:151], v[184:187], v[124:127]
	v_mfma_f32_16x16x32_bf16 v[120:123], v[164:167], v[184:187], v[120:123]
	v_mfma_f32_16x16x32_bf16 v[116:119], v[148:151], v[192:195], v[116:119]
	v_mfma_f32_16x16x32_bf16 v[112:115], v[164:167], v[192:195], v[112:115]
	v_mfma_f32_16x16x32_bf16 v[100:103], v[148:151], v[200:203], v[100:103]
	v_mfma_f32_16x16x32_bf16 v[96:99], v[164:167], v[200:203], v[96:99]
	v_mfma_f32_16x16x32_bf16 v[84:87], v[148:151], v[208:211], v[84:87]
	v_mfma_f32_16x16x32_bf16 v[80:83], v[164:167], v[208:211], v[80:83]
	s_barrier
	s_setprio 0
	s_add_i32 s1, 0, 0x14000
	v_add_u32_e32 v152, s1, v141
	s_add_i32 s17, s17, s85
	ds_read_b128 v[212:215], v152
	ds_read_b128 v[216:219], v152 offset:1024
	ds_read_b128 v[220:223], v152 offset:2048
	ds_read_b128 v[224:227], v152 offset:3072
	v_lshl_add_u64 v[152:153], s[44:45], 0, v[154:155]
	s_mov_b32 m0, s17
	v_lshl_add_u64 v[228:229], s[44:45], 0, v[132:133]
	global_load_lds_dwordx4 v[152:153], off
	s_add_i32 m0, s17, 0x2000
	s_nop 0
	global_load_lds_dwordx4 v[228:229], off
	s_setprio 1
	s_barrier
	s_waitcnt lgkmcnt(0)
	v_mfma_f32_16x16x32_bf16 v[108:111], v[212:215], v[168:171], 0
	v_mfma_f32_16x16x32_bf16 v[104:107], v[220:223], v[168:171], 0
	v_mfma_f32_16x16x32_bf16 v[92:95], v[212:215], v[188:191], 0
	v_mfma_f32_16x16x32_bf16 v[88:91], v[220:223], v[188:191], 0
	v_mfma_f32_16x16x32_bf16 v[76:79], v[212:215], v[196:199], 0
	v_mfma_f32_16x16x32_bf16 v[72:75], v[220:223], v[196:199], 0
	s_mov_b32 m0, s88
	v_mfma_f32_16x16x32_bf16 v[68:71], v[212:215], v[204:207], 0
	v_lshl_add_u64 v[230:231], s[34:35], 0, v[128:129]
	v_mfma_f32_16x16x32_bf16 v[64:67], v[220:223], v[204:207], 0
	v_mfma_f32_16x16x32_bf16 v[108:111], v[216:219], v[184:187], v[108:111]
	v_mfma_f32_16x16x32_bf16 v[104:107], v[224:227], v[184:187], v[104:107]
	v_mfma_f32_16x16x32_bf16 v[92:95], v[216:219], v[192:195], v[92:95]
	v_mfma_f32_16x16x32_bf16 v[88:91], v[224:227], v[192:195], v[88:91]
	v_mfma_f32_16x16x32_bf16 v[76:79], v[216:219], v[200:203], v[76:79]
	v_mfma_f32_16x16x32_bf16 v[72:75], v[224:227], v[200:203], v[72:75]
	v_mfma_f32_16x16x32_bf16 v[68:71], v[216:219], v[208:211], v[68:71]
	v_mfma_f32_16x16x32_bf16 v[64:67], v[224:227], v[208:211], v[64:67]
	s_barrier
	s_setprio 0
	ds_read_b128 v[168:171], v143 offset:16384
	ds_read_b128 v[184:187], v143 offset:17408
	ds_read_b128 v[188:191], v143 offset:18432
	ds_read_b128 v[192:195], v143 offset:19456
	ds_read_b128 v[196:199], v143 offset:20480
	ds_read_b128 v[200:203], v143 offset:21504
	ds_read_b128 v[204:207], v143 offset:22528
	ds_read_b128 v[208:211], v143 offset:23552
	global_load_lds_dwordx4 v[230:231], off
	v_lshl_add_u64 v[232:233], s[34:35], 0, v[130:131]
	s_mov_b32 m0, s89
	s_nop 0
	global_load_lds_dwordx4 v[232:233], off
	s_setprio 1
	s_barrier
	s_waitcnt lgkmcnt(0)
	v_mfma_f32_16x16x32_bf16 v[60:63], v[144:147], v[168:171], 0
	v_mfma_f32_16x16x32_bf16 v[56:59], v[160:163], v[168:171], 0
	v_mfma_f32_16x16x32_bf16 v[52:55], v[144:147], v[188:191], 0
	v_mfma_f32_16x16x32_bf16 v[48:51], v[160:163], v[188:191], 0
	v_mfma_f32_16x16x32_bf16 v[36:39], v[144:147], v[196:199], 0
	v_mfma_f32_16x16x32_bf16 v[32:35], v[160:163], v[196:199], 0
	v_mfma_f32_16x16x32_bf16 v[20:23], v[144:147], v[204:207], 0
	v_mfma_f32_16x16x32_bf16 v[16:19], v[160:163], v[204:207], 0
	v_mfma_f32_16x16x32_bf16 v[60:63], v[148:151], v[184:187], v[60:63]
	v_mfma_f32_16x16x32_bf16 v[56:59], v[164:167], v[184:187], v[56:59]
	v_mfma_f32_16x16x32_bf16 v[52:55], v[148:151], v[192:195], v[52:55]
	v_mfma_f32_16x16x32_bf16 v[48:51], v[164:167], v[192:195], v[48:51]
	v_mfma_f32_16x16x32_bf16 v[36:39], v[148:151], v[200:203], v[36:39]
	v_mfma_f32_16x16x32_bf16 v[32:35], v[164:167], v[200:203], v[32:35]
	v_mfma_f32_16x16x32_bf16 v[20:23], v[148:151], v[208:211], v[20:23]
	v_mfma_f32_16x16x32_bf16 v[16:19], v[164:167], v[208:211], v[16:19]
	s_barrier
; #define PG8_STAGE(bufoff, gbase, voff) do { _Pragma("unroll") for (int _i = 0; _i < 2; ++_i) \
;         __builtin_amdgcn_global_load_lds((const unsigned*)((const char*)(gbase) + (voff)[_i]), (LAS unsigned*)(lds + (bufoff) + ldsw + _i * 8192), 16, 0, 0); } while (0)
; #define PG8_LDA(dst, b, h) do { _Pragma("unroll") for (int m = 0; m < 4; ++m) _Pragma("unroll") for (int k = 0; k < 2; ++k) dst[m][k] = *(const LAS bf16x8*)(lds + PG8_SA(b, h) + aoff + m * 2048 + k * 1024); } while (0)
; #define PG8_LDB(dst, b, h) do { _Pragma("unroll") for (int n = 0; n < 2; ++n) _Pragma("unroll") for (int k = 0; k < 2; ++k) dst[n][k] = *(const LAS bf16x8*)(lds + PG8_SB(b, h) + boff + n * 2048 + k * 1024); } while (0)
; #define PG8_MMA(ai, bj, At, Bt) do { __builtin_amdgcn_s_setprio(1); _Pragma("unroll") for (int m = 0; m < 4; ++m) _Pragma("unroll") for (int n = 0; n < 2; ++n) _Pragma("unroll") for (int k = 0; k < 2; ++k) \
;         acc[ai][bj][m][n] = __builtin_amdgcn_mfma_f32_16x16x32_bf16(Bt[n][k], At[m][k], acc[ai][bj][m][n], 0, 0, 0); __builtin_amdgcn_s_setprio(0); } while (0)
; #define PG8_WAIT_V(n) asm volatile("s_waitcnt vmcnt(" #n ")" ::: "memory")
; #define PG8_WAIT_L(n) asm volatile("s_waitcnt lgkmcnt(" #n ")" ::: "memory")
; #define PG8_BAR __builtin_amdgcn_s_barrier()
; #define PG8_SCHED __builtin_amdgcn_sched_barrier(0)
; template <class Epi, class Sched>
; __device__ __forceinline__ void gemm_phase(LAS unsigned char* lds, const Gemm g, const Sched& S, const Epi& E, int tid) {
;     ...
;             PG8_BAR; PG8_WAIT_L(0); PG8_MMA(1, 0, At, B0); PG8_BAR; PG8_SCHED;
;             PG8_STAGE(PG8_SB(0, 1), b2 + hstep, voffB);
;             PG8_WAIT_V(6); PG8_BAR; PG8_MMA(1, 1, At, B1); PG8_BAR;
;             PG8_LDB(B0, 1, 0); PG8_SCHED; PG8_LDA(At, 1, 0); PG8_STAGE(PG8_SA(0, 1), a2 + hstep, voffA);
;             PG8_WAIT_L(8); PG8_BAR; PG8_WAIT_L(0); PG8_MMA(0, 0, At, B0); PG8_BAR; PG8_SCHED;
;             PG8_LDB(B1, 1, 1); PG8_STAGE(PG8_SB(1, 0), b3, voffB);
;             PG8_BAR; PG8_WAIT_L(0); PG8_MMA(0, 1, At, B1); PG8_BAR;
;             PG8_LDA(At, 1, 1); PG8_STAGE(PG8_SA(1, 0), a3, voffA);
;             PG8_BAR; PG8_WAIT_L(0); PG8_MMA(1, 0, At, B0); PG8_BAR; PG8_SCHED;
	s_setprio 0
	s_add_u32 s44, s44, s6
	s_addc_u32 s45, s45, 0
	s_add_i32 s1, s1, s85
	v_lshl_add_u64 v[234:235], s[44:45], 0, v[154:155]
	s_mov_b32 m0, s1
	v_lshl_add_u64 v[236:237], s[44:45], 0, v[132:133]
	global_load_lds_dwordx4 v[234:235], off
	s_add_i32 m0, s1, 0x2000
	s_nop 0
	global_load_lds_dwordx4 v[236:237], off
	s_waitcnt vmcnt(24)
	s_setprio 1
	s_barrier
	v_mfma_f32_16x16x32_bf16 v[44:47], v[212:215], v[168:171], 0
	v_mfma_f32_16x16x32_bf16 v[40:43], v[220:223], v[168:171], 0
	v_mfma_f32_16x16x32_bf16 v[28:31], v[212:215], v[188:191], 0
	v_mfma_f32_16x16x32_bf16 v[24:27], v[220:223], v[188:191], 0
	v_mfma_f32_16x16x32_bf16 v[12:15], v[212:215], v[196:199], 0
	v_mfma_f32_16x16x32_bf16 v[8:11], v[220:223], v[196:199], 0
	s_add_i32 s1, 0, 0x18000
	v_mfma_f32_16x16x32_bf16 v[4:7], v[212:215], v[204:207], 0
	v_add_u32_e32 v164, s1, v141
	v_mfma_f32_16x16x32_bf16 v[0:3], v[220:223], v[204:207], 0
	v_mfma_f32_16x16x32_bf16 v[44:47], v[216:219], v[184:187], v[44:47]
	v_mfma_f32_16x16x32_bf16 v[40:43], v[224:227], v[184:187], v[40:43]
	v_mfma_f32_16x16x32_bf16 v[28:31], v[216:219], v[192:195], v[28:31]
	v_mfma_f32_16x16x32_bf16 v[24:27], v[224:227], v[192:195], v[24:27]
	v_mfma_f32_16x16x32_bf16 v[12:15], v[216:219], v[200:203], v[12:15]
	v_mfma_f32_16x16x32_bf16 v[8:11], v[224:227], v[200:203], v[8:11]
	v_mfma_f32_16x16x32_bf16 v[4:7], v[216:219], v[208:211], v[4:7]
	v_mfma_f32_16x16x32_bf16 v[0:3], v[224:227], v[208:211], v[0:3]
	s_barrier
	s_setprio 0
	ds_read_b128 v[144:147], v164
	ds_read_b128 v[148:151], v164 offset:1024
	ds_read_b128 v[160:163], v164 offset:2048
	ds_read_b128 v[164:167], v164 offset:3072
	s_add_u32 s34, s34, s6
	s_addc_u32 s35, s35, 0
	s_mov_b32 m0, s90
	v_lshl_add_u64 v[212:213], s[34:35], 0, v[128:129]
	ds_read_b128 v[168:171], v143 offset:32768
	ds_read_b128 v[188:191], v143 offset:34816
	ds_read_b128 v[196:199], v143 offset:36864
	ds_read_b128 v[204:207], v143 offset:38912
	global_load_lds_dwordx4 v[212:213], off
	v_lshl_add_u64 v[212:213], s[34:35], 0, v[130:131]
	s_mov_b32 m0, s91
	s_nop 0
	global_load_lds_dwordx4 v[212:213], off
	s_waitcnt lgkmcnt(4)
	s_setprio 1
	s_barrier
	s_waitcnt lgkmcnt(0)
	v_mfma_f32_16x16x32_bf16 v[124:127], v[144:147], v[168:171], v[124:127]
	ds_read_b128 v[184:187], v143 offset:33792
	v_mfma_f32_16x16x32_bf16 v[120:123], v[160:163], v[168:171], v[120:123]
	ds_read_b128 v[192:195], v143 offset:35840
	v_mfma_f32_16x16x32_bf16 v[116:119], v[144:147], v[188:191], v[116:119]
	ds_read_b128 v[200:203], v143 offset:37888
	v_mfma_f32_16x16x32_bf16 v[112:115], v[160:163], v[188:191], v[112:115]
	ds_read_b128 v[208:211], v143 offset:39936
	v_mfma_f32_16x16x32_bf16 v[100:103], v[144:147], v[196:199], v[100:103]
	v_mfma_f32_16x16x32_bf16 v[96:99], v[160:163], v[196:199], v[96:99]
	v_mfma_f32_16x16x32_bf16 v[84:87], v[144:147], v[204:207], v[84:87]
	v_mfma_f32_16x16x32_bf16 v[80:83], v[160:163], v[204:207], v[80:83]
	s_waitcnt lgkmcnt(0)
	v_mfma_f32_16x16x32_bf16 v[124:127], v[148:151], v[184:187], v[124:127]
	v_mfma_f32_16x16x32_bf16 v[120:123], v[164:167], v[184:187], v[120:123]
	v_mfma_f32_16x16x32_bf16 v[116:119], v[148:151], v[192:195], v[116:119]
	v_mfma_f32_16x16x32_bf16 v[112:115], v[164:167], v[192:195], v[112:115]
	v_mfma_f32_16x16x32_bf16 v[100:103], v[148:151], v[200:203], v[100:103]
	v_mfma_f32_16x16x32_bf16 v[96:99], v[164:167], v[200:203], v[96:99]
	v_mfma_f32_16x16x32_bf16 v[84:87], v[148:151], v[208:211], v[84:87]
	v_mfma_f32_16x16x32_bf16 v[80:83], v[164:167], v[208:211], v[80:83]
	s_barrier
	s_setprio 0
	s_add_i32 s17, 0, 0x1c000
	s_add_i32 s1, s1, s85
	v_add_u32_e32 v183, s17, v141
	v_lshl_add_u64 v[152:153], v[152:153], 0, s[8:9]
	s_mov_b32 m0, s1
	ds_read_b128 v[212:215], v183
	ds_read_b128 v[216:219], v183 offset:1024
	ds_read_b128 v[220:223], v183 offset:2048
	ds_read_b128 v[224:227], v183 offset:3072
	global_load_lds_dwordx4 v[152:153], off
	v_lshl_add_u64 v[152:153], v[228:229], 0, s[8:9]
	s_add_i32 m0, s1, 0x2000
	s_nop 0
	global_load_lds_dwordx4 v[152:153], off
	s_waitcnt vmcnt(10)
	s_setprio 1
	s_barrier
	s_waitcnt lgkmcnt(0)
	v_mfma_f32_16x16x32_bf16 v[108:111], v[212:215], v[168:171], v[108:111]
	v_mfma_f32_16x16x32_bf16 v[104:107], v[220:223], v[168:171], v[104:107]
	v_mfma_f32_16x16x32_bf16 v[92:95], v[212:215], v[188:191], v[92:95]
	v_mfma_f32_16x16x32_bf16 v[88:91], v[220:223], v[188:191], v[88:91]
	v_mfma_f32_16x16x32_bf16 v[76:79], v[212:215], v[196:199], v[76:79]
	v_mfma_f32_16x16x32_bf16 v[72:75], v[220:223], v[196:199], v[72:75]
	s_mov_b32 m0, s92
	v_mfma_f32_16x16x32_bf16 v[68:71], v[212:215], v[204:207], v[68:71]
	v_lshl_add_u64 v[152:153], v[230:231], 0, s[8:9]
	v_mfma_f32_16x16x32_bf16 v[64:67], v[220:223], v[204:207], v[64:67]
	v_mfma_f32_16x16x32_bf16 v[108:111], v[216:219], v[184:187], v[108:111]
	v_mfma_f32_16x16x32_bf16 v[104:107], v[224:227], v[184:187], v[104:107]
	v_mfma_f32_16x16x32_bf16 v[92:95], v[216:219], v[192:195], v[92:95]
	v_mfma_f32_16x16x32_bf16 v[88:91], v[224:227], v[192:195], v[88:91]
	v_mfma_f32_16x16x32_bf16 v[76:79], v[216:219], v[200:203], v[76:79]
	v_mfma_f32_16x16x32_bf16 v[72:75], v[224:227], v[200:203], v[72:75]
	v_mfma_f32_16x16x32_bf16 v[68:71], v[216:219], v[208:211], v[68:71]
	v_mfma_f32_16x16x32_bf16 v[64:67], v[224:227], v[208:211], v[64:67]
	s_barrier
	s_setprio 0
	ds_read_b128 v[168:171], v143 offset:49152
	ds_read_b128 v[184:187], v143 offset:50176
	ds_read_b128 v[188:191], v143 offset:51200
	ds_read_b128 v[192:195], v143 offset:52224
	ds_read_b128 v[196:199], v143 offset:53248
	ds_read_b128 v[200:203], v143 offset:54272
	ds_read_b128 v[204:207], v143 offset:55296
	ds_read_b128 v[208:211], v143 offset:56320
	global_load_lds_dwordx4 v[152:153], off
	v_lshl_add_u64 v[152:153], v[232:233], 0, s[8:9]
	s_mov_b32 m0, s93
	s_nop 0
	global_load_lds_dwordx4 v[152:153], off
	s_setprio 1
	s_barrier
; #define PG8_STAGE(bufoff, gbase, voff) do { _Pragma("unroll") for (int _i = 0; _i < 2; ++_i) \
;         __builtin_amdgcn_global_load_lds((const unsigned*)((const char*)(gbase) + (voff)[_i]), (LAS unsigned*)(lds + (bufoff) + ldsw + _i * 8192), 16, 0, 0); } while (0)
; #define PG8_LDA(dst, b, h) do { _Pragma("unroll") for (int m = 0; m < 4; ++m) _Pragma("unroll") for (int k = 0; k < 2; ++k) dst[m][k] = *(const LAS bf16x8*)(lds + PG8_SA(b, h) + aoff + m * 2048 + k * 1024); } while (0)
; #define PG8_LDB(dst, b, h) do { _Pragma("unroll") for (int n = 0; n < 2; ++n) _Pragma("unroll") for (int k = 0; k < 2; ++k) dst[n][k] = *(const LAS bf16x8*)(lds + PG8_SB(b, h) + boff + n * 2048 + k * 1024); } while (0)
; #define PG8_MMA(ai, bj, At, Bt) do { __builtin_amdgcn_s_setprio(1); _Pragma("unroll") for (int m = 0; m < 4; ++m) _Pragma("unroll") for (int n = 0; n < 2; ++n) _Pragma("unroll") for (int k = 0; k < 2; ++k) \
;         acc[ai][bj][m][n] = __builtin_amdgcn_mfma_f32_16x16x32_bf16(Bt[n][k], At[m][k], acc[ai][bj][m][n], 0, 0, 0); __builtin_amdgcn_s_setprio(0); } while (0)
; #define PG8_WAIT_V(n) asm volatile("s_waitcnt vmcnt(" #n ")" ::: "memory")
; #define PG8_WAIT_L(n) asm volatile("s_waitcnt lgkmcnt(" #n ")" ::: "memory")
; #define PG8_BAR __builtin_amdgcn_s_barrier()
; #define PG8_SCHED __builtin_amdgcn_sched_barrier(0)
; template <class Epi, class Sched>
; __device__ __forceinline__ void gemm_phase(LAS unsigned char* lds, const Gemm g, const Sched& S, const Epi& E, int tid) {
;     ...
;             const bool last = (t == nt - 2);
;             const char* a1 = cA + (size_t)(t + 1) * kstep;
;             const char* a2 = last ? nA : cA + (size_t)(t + 2) * kstep; const char* b2 = last ? nB : cB + (size_t)(t + 2) * kstep;
;             const char* a3 = a2 + kstep; const char* b3 = b2 + kstep;
;             PG8_LDB(B0, 0, 0); PG8_SCHED; PG8_LDA(At, 0, 0); PG8_STAGE(PG8_SA(1, 1), a1 + hstep, voffA);
;             PG8_WAIT_L(8); PG8_BAR; PG8_WAIT_L(0); PG8_MMA(0, 0, At, B0); PG8_BAR; PG8_SCHED;
;             PG8_LDB(B1, 0, 1); PG8_STAGE(PG8_SB(0, 0), b2, voffB);
;             PG8_BAR; PG8_WAIT_L(0); PG8_MMA(0, 1, At, B1); PG8_BAR;
;     ...
;             PG8_BAR; PG8_WAIT_L(0); PG8_MMA(1, 0, At, B0); PG8_BAR; PG8_SCHED;
;             PG8_STAGE(PG8_SB(1, 1), b3 + hstep, voffB);
;             PG8_WAIT_V(6); PG8_BAR; PG8_MMA(1, 1, At, B1); PG8_BAR;
	s_waitcnt lgkmcnt(0)
	v_mfma_f32_16x16x32_bf16 v[60:63], v[144:147], v[168:171], v[60:63]
	v_mfma_f32_16x16x32_bf16 v[56:59], v[160:163], v[168:171], v[56:59]
	v_mfma_f32_16x16x32_bf16 v[52:55], v[144:147], v[188:191], v[52:55]
	v_mfma_f32_16x16x32_bf16 v[48:51], v[160:163], v[188:191], v[48:51]
	v_mfma_f32_16x16x32_bf16 v[36:39], v[144:147], v[196:199], v[36:39]
	v_mfma_f32_16x16x32_bf16 v[32:35], v[160:163], v[196:199], v[32:35]
	v_mfma_f32_16x16x32_bf16 v[20:23], v[144:147], v[204:207], v[20:23]
	v_mfma_f32_16x16x32_bf16 v[16:19], v[160:163], v[204:207], v[16:19]
	v_mfma_f32_16x16x32_bf16 v[60:63], v[148:151], v[184:187], v[60:63]
	v_mfma_f32_16x16x32_bf16 v[56:59], v[164:167], v[184:187], v[56:59]
	v_mfma_f32_16x16x32_bf16 v[52:55], v[148:151], v[192:195], v[52:55]
	v_mfma_f32_16x16x32_bf16 v[48:51], v[164:167], v[192:195], v[48:51]
	v_mfma_f32_16x16x32_bf16 v[36:39], v[148:151], v[200:203], v[36:39]
	v_mfma_f32_16x16x32_bf16 v[32:35], v[164:167], v[200:203], v[32:35]
	v_mfma_f32_16x16x32_bf16 v[20:23], v[148:151], v[208:211], v[20:23]
	v_mfma_f32_16x16x32_bf16 v[16:19], v[164:167], v[208:211], v[16:19]
	s_barrier
	s_setprio 0
	s_add_i32 s1, s17, s85
	v_lshl_add_u64 v[144:145], v[234:235], 0, s[8:9]
	s_mov_b32 m0, s1
	s_nop 0
	global_load_lds_dwordx4 v[144:145], off
	v_lshl_add_u64 v[144:145], v[236:237], 0, s[8:9]
	s_add_i32 m0, s1, 0x2000
	s_nop 0
	global_load_lds_dwordx4 v[144:145], off
	s_waitcnt vmcnt(6)
	s_setprio 1
	s_barrier
	v_mfma_f32_16x16x32_bf16 v[44:47], v[212:215], v[168:171], v[44:47]
	v_mfma_f32_16x16x32_bf16 v[40:43], v[220:223], v[168:171], v[40:43]
	v_mfma_f32_16x16x32_bf16 v[28:31], v[212:215], v[188:191], v[28:31]
	v_mfma_f32_16x16x32_bf16 v[24:27], v[220:223], v[188:191], v[24:27]
	v_mfma_f32_16x16x32_bf16 v[12:15], v[212:215], v[196:199], v[12:15]
	v_mfma_f32_16x16x32_bf16 v[8:11], v[220:223], v[196:199], v[8:11]
	s_add_u32 vcc_lo, vcc_lo, 0x100
	v_mfma_f32_16x16x32_bf16 v[4:7], v[212:215], v[204:207], v[4:7]
	s_addc_u32 vcc_hi, vcc_hi, 0
	v_mfma_f32_16x16x32_bf16 v[0:3], v[220:223], v[204:207], v[0:3]
	s_add_u32 s96, s96, 0x100
	v_mfma_f32_16x16x32_bf16 v[44:47], v[216:219], v[184:187], v[44:47]
	s_addc_u32 s65, s65, 0
	v_mfma_f32_16x16x32_bf16 v[40:43], v[224:227], v[184:187], v[40:43]
	s_cmp_ge_u32 s0, s94
	v_mfma_f32_16x16x32_bf16 v[28:31], v[216:219], v[192:195], v[28:31]
	s_mov_b32 s34, s0
	v_mfma_f32_16x16x32_bf16 v[24:27], v[224:227], v[192:195], v[24:27]
	v_mfma_f32_16x16x32_bf16 v[12:15], v[216:219], v[200:203], v[12:15]
	v_mfma_f32_16x16x32_bf16 v[8:11], v[224:227], v[200:203], v[8:11]
	v_mfma_f32_16x16x32_bf16 v[4:7], v[216:219], v[208:211], v[4:7]
	v_mfma_f32_16x16x32_bf16 v[0:3], v[224:227], v[208:211], v[0:3]
	s_barrier
	s_setprio 0
	s_cbranch_scc1 .Lpeel_exit_plain
.LBB0_100:
	s_add_i32 s0, s34, 2
	s_add_u32 s1, vcc_lo, 0x80
	s_addc_u32 s35, vcc_hi, 0
	s_add_i32 s17, 0, 0x10000
	v_add_u32_e32 v152, s17, v141
	ds_read_b128 v[144:147], v152
	ds_read_b128 v[148:151], v152 offset:1024
	ds_read_b128 v[160:163], v152 offset:2048
	ds_read_b128 v[164:167], v152 offset:3072
	s_cmp_eq_u32 s95, s34
	s_cselect_b32 s34, s38, s1
	s_cselect_b32 s35, s39, s35
	s_cselect_b32 s45, s41, s65
	s_cselect_b32 s44, s40, s96
	v_lshl_add_u64 v[152:153], vcc, 0, v[134:135]
	s_add_i32 m0, s88, 0xc000
	ds_read_b128 v[168:171], v143
	ds_read_b128 v[188:191], v143 offset:2048
	ds_read_b128 v[196:199], v143 offset:4096
	ds_read_b128 v[204:207], v143 offset:6144
	global_load_lds_dwordx4 v[152:153], off
	v_lshl_add_u64 v[152:153], vcc, 0, v[136:137]
	s_add_i32 m0, s88, 0xe000
	s_nop 0
	global_load_lds_dwordx4 v[152:153], off
	s_waitcnt lgkmcnt(4)
	s_setprio 1
	s_barrier
	s_waitcnt lgkmcnt(0)
	v_mfma_f32_16x16x32_bf16 v[124:127], v[144:147], v[168:171], v[124:127]
	ds_read_b128 v[184:187], v143 offset:1024
	v_mfma_f32_16x16x32_bf16 v[120:123], v[160:163], v[168:171], v[120:123]
	ds_read_b128 v[192:195], v143 offset:3072
	v_mfma_f32_16x16x32_bf16 v[116:119], v[144:147], v[188:191], v[116:119]
	ds_read_b128 v[200:203], v143 offset:5120
	v_mfma_f32_16x16x32_bf16 v[112:115], v[160:163], v[188:191], v[112:115]
	ds_read_b128 v[208:211], v143 offset:7168
	v_mfma_f32_16x16x32_bf16 v[100:103], v[144:147], v[196:199], v[100:103]
	v_mfma_f32_16x16x32_bf16 v[96:99], v[160:163], v[196:199], v[96:99]
	v_mfma_f32_16x16x32_bf16 v[84:87], v[144:147], v[204:207], v[84:87]
	v_mfma_f32_16x16x32_bf16 v[80:83], v[160:163], v[204:207], v[80:83]
	s_waitcnt lgkmcnt(0)
	v_mfma_f32_16x16x32_bf16 v[124:127], v[148:151], v[184:187], v[124:127]
	v_mfma_f32_16x16x32_bf16 v[120:123], v[164:167], v[184:187], v[120:123]
	v_mfma_f32_16x16x32_bf16 v[116:119], v[148:151], v[192:195], v[116:119]
	v_mfma_f32_16x16x32_bf16 v[112:115], v[164:167], v[192:195], v[112:115]
	v_mfma_f32_16x16x32_bf16 v[100:103], v[148:151], v[200:203], v[100:103]
	v_mfma_f32_16x16x32_bf16 v[96:99], v[164:167], v[200:203], v[96:99]
	v_mfma_f32_16x16x32_bf16 v[84:87], v[148:151], v[208:211], v[84:87]
	v_mfma_f32_16x16x32_bf16 v[80:83], v[164:167], v[208:211], v[80:83]
	s_barrier
	s_setprio 0
	s_add_i32 s1, 0, 0x14000
	v_add_u32_e32 v152, s1, v141
	s_add_i32 s17, s17, s85
	ds_read_b128 v[212:215], v152
	ds_read_b128 v[216:219], v152 offset:1024
	ds_read_b128 v[220:223], v152 offset:2048
	ds_read_b128 v[224:227], v152 offset:3072
	v_lshl_add_u64 v[152:153], s[44:45], 0, v[154:155]
	s_mov_b32 m0, s17
	v_lshl_add_u64 v[228:229], s[44:45], 0, v[132:133]
	global_load_lds_dwordx4 v[152:153], off
	s_add_i32 m0, s17, 0x2000
	s_nop 0
	global_load_lds_dwordx4 v[228:229], off
	s_setprio 1
	s_barrier
; #define PG8_STAGE(bufoff, gbase, voff) do { _Pragma("unroll") for (int _i = 0; _i < 2; ++_i) \
;         __builtin_amdgcn_global_load_lds((const unsigned*)((const char*)(gbase) + (voff)[_i]), (LAS unsigned*)(lds + (bufoff) + ldsw + _i * 8192), 16, 0, 0); } while (0)
; #define PG8_LDA(dst, b, h) do { _Pragma("unroll") for (int m = 0; m < 4; ++m) _Pragma("unroll") for (int k = 0; k < 2; ++k) dst[m][k] = *(const LAS bf16x8*)(lds + PG8_SA(b, h) + aoff + m * 2048 + k * 1024); } while (0)
; #define PG8_LDB(dst, b, h) do { _Pragma("unroll") for (int n = 0; n < 2; ++n) _Pragma("unroll") for (int k = 0; k < 2; ++k) dst[n][k] = *(const LAS bf16x8*)(lds + PG8_SB(b, h) + boff + n * 2048 + k * 1024); } while (0)
; #define PG8_MMA(ai, bj, At, Bt) do { __builtin_amdgcn_s_setprio(1); _Pragma("unroll") for (int m = 0; m < 4; ++m) _Pragma("unroll") for (int n = 0; n < 2; ++n) _Pragma("unroll") for (int k = 0; k < 2; ++k) \
;         acc[ai][bj][m][n] = __builtin_amdgcn_mfma_f32_16x16x32_bf16(Bt[n][k], At[m][k], acc[ai][bj][m][n], 0, 0, 0); __builtin_amdgcn_s_setprio(0); } while (0)
; #define PG8_WAIT_V(n) asm volatile("s_waitcnt vmcnt(" #n ")" ::: "memory")
; #define PG8_WAIT_L(n) asm volatile("s_waitcnt lgkmcnt(" #n ")" ::: "memory")
; #define PG8_BAR __builtin_amdgcn_s_barrier()
; #define PG8_SCHED __builtin_amdgcn_sched_barrier(0)
; template <class Epi, class Sched>
; __device__ __forceinline__ void gemm_phase(LAS unsigned char* lds, const Gemm g, const Sched& S, const Epi& E, int tid) {
;     ...
;             PG8_BAR; PG8_WAIT_L(0); PG8_MMA(0, 1, At, B1); PG8_BAR;
;             PG8_LDA(At, 0, 1); PG8_STAGE(PG8_SA(0, 0), a2, voffA);
;             PG8_BAR; PG8_WAIT_L(0); PG8_MMA(1, 0, At, B0); PG8_BAR; PG8_SCHED;
;             PG8_STAGE(PG8_SB(0, 1), b2 + hstep, voffB);
;             PG8_WAIT_V(6); PG8_BAR; PG8_MMA(1, 1, At, B1); PG8_BAR;
;             PG8_LDB(B0, 1, 0); PG8_SCHED; PG8_LDA(At, 1, 0); PG8_STAGE(PG8_SA(0, 1), a2 + hstep, voffA);
	s_waitcnt lgkmcnt(0)
	v_mfma_f32_16x16x32_bf16 v[108:111], v[212:215], v[168:171], v[108:111]
	v_mfma_f32_16x16x32_bf16 v[104:107], v[220:223], v[168:171], v[104:107]
	v_mfma_f32_16x16x32_bf16 v[92:95], v[212:215], v[188:191], v[92:95]
	v_mfma_f32_16x16x32_bf16 v[88:91], v[220:223], v[188:191], v[88:91]
	v_mfma_f32_16x16x32_bf16 v[76:79], v[212:215], v[196:199], v[76:79]
	v_mfma_f32_16x16x32_bf16 v[72:75], v[220:223], v[196:199], v[72:75]
	s_mov_b32 m0, s88
	v_mfma_f32_16x16x32_bf16 v[68:71], v[212:215], v[204:207], v[68:71]
	v_lshl_add_u64 v[230:231], s[34:35], 0, v[128:129]
	v_mfma_f32_16x16x32_bf16 v[64:67], v[220:223], v[204:207], v[64:67]
	v_mfma_f32_16x16x32_bf16 v[108:111], v[216:219], v[184:187], v[108:111]
	v_mfma_f32_16x16x32_bf16 v[104:107], v[224:227], v[184:187], v[104:107]
	v_mfma_f32_16x16x32_bf16 v[92:95], v[216:219], v[192:195], v[92:95]
	v_mfma_f32_16x16x32_bf16 v[88:91], v[224:227], v[192:195], v[88:91]
	v_mfma_f32_16x16x32_bf16 v[76:79], v[216:219], v[200:203], v[76:79]
	v_mfma_f32_16x16x32_bf16 v[72:75], v[224:227], v[200:203], v[72:75]
	v_mfma_f32_16x16x32_bf16 v[68:71], v[216:219], v[208:211], v[68:71]
	v_mfma_f32_16x16x32_bf16 v[64:67], v[224:227], v[208:211], v[64:67]
	s_barrier
	s_setprio 0
	ds_read_b128 v[168:171], v143 offset:16384
	ds_read_b128 v[184:187], v143 offset:17408
	ds_read_b128 v[188:191], v143 offset:18432
	ds_read_b128 v[192:195], v143 offset:19456
	ds_read_b128 v[196:199], v143 offset:20480
	ds_read_b128 v[200:203], v143 offset:21504
	ds_read_b128 v[204:207], v143 offset:22528
	ds_read_b128 v[208:211], v143 offset:23552
	global_load_lds_dwordx4 v[230:231], off
	v_lshl_add_u64 v[232:233], s[34:35], 0, v[130:131]
	s_mov_b32 m0, s89
	s_nop 0
	global_load_lds_dwordx4 v[232:233], off
	s_setprio 1
	s_barrier
	s_waitcnt lgkmcnt(0)
	v_mfma_f32_16x16x32_bf16 v[60:63], v[144:147], v[168:171], v[60:63]
	v_mfma_f32_16x16x32_bf16 v[56:59], v[160:163], v[168:171], v[56:59]
	v_mfma_f32_16x16x32_bf16 v[52:55], v[144:147], v[188:191], v[52:55]
	v_mfma_f32_16x16x32_bf16 v[48:51], v[160:163], v[188:191], v[48:51]
	v_mfma_f32_16x16x32_bf16 v[36:39], v[144:147], v[196:199], v[36:39]
	v_mfma_f32_16x16x32_bf16 v[32:35], v[160:163], v[196:199], v[32:35]
	v_mfma_f32_16x16x32_bf16 v[20:23], v[144:147], v[204:207], v[20:23]
	v_mfma_f32_16x16x32_bf16 v[16:19], v[160:163], v[204:207], v[16:19]
	v_mfma_f32_16x16x32_bf16 v[60:63], v[148:151], v[184:187], v[60:63]
	v_mfma_f32_16x16x32_bf16 v[56:59], v[164:167], v[184:187], v[56:59]
	v_mfma_f32_16x16x32_bf16 v[52:55], v[148:151], v[192:195], v[52:55]
	v_mfma_f32_16x16x32_bf16 v[48:51], v[164:167], v[192:195], v[48:51]
	v_mfma_f32_16x16x32_bf16 v[36:39], v[148:151], v[200:203], v[36:39]
	v_mfma_f32_16x16x32_bf16 v[32:35], v[164:167], v[200:203], v[32:35]
	v_mfma_f32_16x16x32_bf16 v[20:23], v[148:151], v[208:211], v[20:23]
	v_mfma_f32_16x16x32_bf16 v[16:19], v[164:167], v[208:211], v[16:19]
	s_barrier
	s_setprio 0
	s_add_u32 s44, s44, s6
	s_addc_u32 s45, s45, 0
	s_add_i32 s1, s1, s85
	v_lshl_add_u64 v[234:235], s[44:45], 0, v[154:155]
	s_mov_b32 m0, s1
	v_lshl_add_u64 v[236:237], s[44:45], 0, v[132:133]
	global_load_lds_dwordx4 v[234:235], off
	s_add_i32 m0, s1, 0x2000
	s_nop 0
	global_load_lds_dwordx4 v[236:237], off
	s_waitcnt vmcnt(6)
	s_setprio 1
	s_barrier
	v_mfma_f32_16x16x32_bf16 v[44:47], v[212:215], v[168:171], v[44:47]
	v_mfma_f32_16x16x32_bf16 v[40:43], v[220:223], v[168:171], v[40:43]
	v_mfma_f32_16x16x32_bf16 v[28:31], v[212:215], v[188:191], v[28:31]
	v_mfma_f32_16x16x32_bf16 v[24:27], v[220:223], v[188:191], v[24:27]
	v_mfma_f32_16x16x32_bf16 v[12:15], v[212:215], v[196:199], v[12:15]
	v_mfma_f32_16x16x32_bf16 v[8:11], v[220:223], v[196:199], v[8:11]
	s_add_i32 s1, 0, 0x18000
	v_mfma_f32_16x16x32_bf16 v[4:7], v[212:215], v[204:207], v[4:7]
	v_add_u32_e32 v164, s1, v141
	v_mfma_f32_16x16x32_bf16 v[0:3], v[220:223], v[204:207], v[0:3]
	v_mfma_f32_16x16x32_bf16 v[44:47], v[216:219], v[184:187], v[44:47]
	v_mfma_f32_16x16x32_bf16 v[40:43], v[224:227], v[184:187], v[40:43]
	v_mfma_f32_16x16x32_bf16 v[28:31], v[216:219], v[192:195], v[28:31]
	v_mfma_f32_16x16x32_bf16 v[24:27], v[224:227], v[192:195], v[24:27]
	v_mfma_f32_16x16x32_bf16 v[12:15], v[216:219], v[200:203], v[12:15]
	v_mfma_f32_16x16x32_bf16 v[8:11], v[224:227], v[200:203], v[8:11]
	v_mfma_f32_16x16x32_bf16 v[4:7], v[216:219], v[208:211], v[4:7]
	v_mfma_f32_16x16x32_bf16 v[0:3], v[224:227], v[208:211], v[0:3]
	s_barrier
	s_setprio 0
	ds_read_b128 v[144:147], v164
	ds_read_b128 v[148:151], v164 offset:1024
	ds_read_b128 v[160:163], v164 offset:2048
	ds_read_b128 v[164:167], v164 offset:3072
	s_add_u32 s34, s34, s6
	s_addc_u32 s35, s35, 0
	s_mov_b32 m0, s90
	v_lshl_add_u64 v[212:213], s[34:35], 0, v[128:129]
	ds_read_b128 v[168:171], v143 offset:32768
	ds_read_b128 v[188:191], v143 offset:34816
	ds_read_b128 v[196:199], v143 offset:36864
	ds_read_b128 v[204:207], v143 offset:38912
	global_load_lds_dwordx4 v[212:213], off
	v_lshl_add_u64 v[212:213], s[34:35], 0, v[130:131]
	s_mov_b32 m0, s91
	s_nop 0
	global_load_lds_dwordx4 v[212:213], off
	s_waitcnt lgkmcnt(4)
	s_setprio 1
	s_barrier
; #define PG8_STAGE(bufoff, gbase, voff) do { _Pragma("unroll") for (int _i = 0; _i < 2; ++_i) \
;         __builtin_amdgcn_global_load_lds((const unsigned*)((const char*)(gbase) + (voff)[_i]), (LAS unsigned*)(lds + (bufoff) + ldsw + _i * 8192), 16, 0, 0); } while (0)
; #define PG8_LDA(dst, b, h) do { _Pragma("unroll") for (int m = 0; m < 4; ++m) _Pragma("unroll") for (int k = 0; k < 2; ++k) dst[m][k] = *(const LAS bf16x8*)(lds + PG8_SA(b, h) + aoff + m * 2048 + k * 1024); } while (0)
; #define PG8_LDB(dst, b, h) do { _Pragma("unroll") for (int n = 0; n < 2; ++n) _Pragma("unroll") for (int k = 0; k < 2; ++k) dst[n][k] = *(const LAS bf16x8*)(lds + PG8_SB(b, h) + boff + n * 2048 + k * 1024); } while (0)
; #define PG8_MMA(ai, bj, At, Bt) do { __builtin_amdgcn_s_setprio(1); _Pragma("unroll") for (int m = 0; m < 4; ++m) _Pragma("unroll") for (int n = 0; n < 2; ++n) _Pragma("unroll") for (int k = 0; k < 2; ++k) \
;         acc[ai][bj][m][n] = __builtin_amdgcn_mfma_f32_16x16x32_bf16(Bt[n][k], At[m][k], acc[ai][bj][m][n], 0, 0, 0); __builtin_amdgcn_s_setprio(0); } while (0)
; #define PG8_WAIT_V(n) asm volatile("s_waitcnt vmcnt(" #n ")" ::: "memory")
; #define PG8_WAIT_L(n) asm volatile("s_waitcnt lgkmcnt(" #n ")" ::: "memory")
; #define PG8_BAR __builtin_amdgcn_s_barrier()
; #define PG8_SCHED __builtin_amdgcn_sched_barrier(0)
; template <class Epi, class Sched>
; __device__ __forceinline__ void gemm_phase(LAS unsigned char* lds, const Gemm g, const Sched& S, const Epi& E, int tid) {
;     ...
;             PG8_WAIT_L(8); PG8_BAR; PG8_WAIT_L(0); PG8_MMA(0, 0, At, B0); PG8_BAR; PG8_SCHED;
;             PG8_LDB(B1, 1, 1); PG8_STAGE(PG8_SB(1, 0), b3, voffB);
;             PG8_BAR; PG8_WAIT_L(0); PG8_MMA(0, 1, At, B1); PG8_BAR;
;             PG8_LDA(At, 1, 1); PG8_STAGE(PG8_SA(1, 0), a3, voffA);
;             PG8_BAR; PG8_WAIT_L(0); PG8_MMA(1, 0, At, B0); PG8_BAR; PG8_SCHED;
;             PG8_STAGE(PG8_SB(1, 1), b3 + hstep, voffB);
;             PG8_WAIT_V(6); PG8_BAR; PG8_MMA(1, 1, At, B1); PG8_BAR;
;         }
	s_waitcnt lgkmcnt(0)
	v_mfma_f32_16x16x32_bf16 v[124:127], v[144:147], v[168:171], v[124:127]
	ds_read_b128 v[184:187], v143 offset:33792
	v_mfma_f32_16x16x32_bf16 v[120:123], v[160:163], v[168:171], v[120:123]
	ds_read_b128 v[192:195], v143 offset:35840
	v_mfma_f32_16x16x32_bf16 v[116:119], v[144:147], v[188:191], v[116:119]
	ds_read_b128 v[200:203], v143 offset:37888
	v_mfma_f32_16x16x32_bf16 v[112:115], v[160:163], v[188:191], v[112:115]
	ds_read_b128 v[208:211], v143 offset:39936
	v_mfma_f32_16x16x32_bf16 v[100:103], v[144:147], v[196:199], v[100:103]
	v_mfma_f32_16x16x32_bf16 v[96:99], v[160:163], v[196:199], v[96:99]
	v_mfma_f32_16x16x32_bf16 v[84:87], v[144:147], v[204:207], v[84:87]
	v_mfma_f32_16x16x32_bf16 v[80:83], v[160:163], v[204:207], v[80:83]
	s_waitcnt lgkmcnt(0)
	v_mfma_f32_16x16x32_bf16 v[124:127], v[148:151], v[184:187], v[124:127]
	v_mfma_f32_16x16x32_bf16 v[120:123], v[164:167], v[184:187], v[120:123]
	v_mfma_f32_16x16x32_bf16 v[116:119], v[148:151], v[192:195], v[116:119]
	v_mfma_f32_16x16x32_bf16 v[112:115], v[164:167], v[192:195], v[112:115]
	v_mfma_f32_16x16x32_bf16 v[100:103], v[148:151], v[200:203], v[100:103]
	v_mfma_f32_16x16x32_bf16 v[96:99], v[164:167], v[200:203], v[96:99]
	v_mfma_f32_16x16x32_bf16 v[84:87], v[148:151], v[208:211], v[84:87]
	v_mfma_f32_16x16x32_bf16 v[80:83], v[164:167], v[208:211], v[80:83]
	s_barrier
	s_setprio 0
	s_add_i32 s17, 0, 0x1c000
	s_add_i32 s1, s1, s85
	v_add_u32_e32 v183, s17, v141
	v_lshl_add_u64 v[152:153], v[152:153], 0, s[8:9]
	s_mov_b32 m0, s1
	ds_read_b128 v[212:215], v183
	ds_read_b128 v[216:219], v183 offset:1024
	ds_read_b128 v[220:223], v183 offset:2048
	ds_read_b128 v[224:227], v183 offset:3072
	global_load_lds_dwordx4 v[152:153], off
	v_lshl_add_u64 v[152:153], v[228:229], 0, s[8:9]
	s_add_i32 m0, s1, 0x2000
	s_nop 0
	global_load_lds_dwordx4 v[152:153], off
	s_setprio 1
	s_barrier
	s_waitcnt lgkmcnt(0)
	v_mfma_f32_16x16x32_bf16 v[108:111], v[212:215], v[168:171], v[108:111]
	v_mfma_f32_16x16x32_bf16 v[104:107], v[220:223], v[168:171], v[104:107]
	v_mfma_f32_16x16x32_bf16 v[92:95], v[212:215], v[188:191], v[92:95]
	v_mfma_f32_16x16x32_bf16 v[88:91], v[220:223], v[188:191], v[88:91]
	v_mfma_f32_16x16x32_bf16 v[76:79], v[212:215], v[196:199], v[76:79]
	v_mfma_f32_16x16x32_bf16 v[72:75], v[220:223], v[196:199], v[72:75]
	s_mov_b32 m0, s92
	v_mfma_f32_16x16x32_bf16 v[68:71], v[212:215], v[204:207], v[68:71]
	v_lshl_add_u64 v[152:153], v[230:231], 0, s[8:9]
	v_mfma_f32_16x16x32_bf16 v[64:67], v[220:223], v[204:207], v[64:67]
	v_mfma_f32_16x16x32_bf16 v[108:111], v[216:219], v[184:187], v[108:111]
	v_mfma_f32_16x16x32_bf16 v[104:107], v[224:227], v[184:187], v[104:107]
	v_mfma_f32_16x16x32_bf16 v[92:95], v[216:219], v[192:195], v[92:95]
	v_mfma_f32_16x16x32_bf16 v[88:91], v[224:227], v[192:195], v[88:91]
	v_mfma_f32_16x16x32_bf16 v[76:79], v[216:219], v[200:203], v[76:79]
	v_mfma_f32_16x16x32_bf16 v[72:75], v[224:227], v[200:203], v[72:75]
	v_mfma_f32_16x16x32_bf16 v[68:71], v[216:219], v[208:211], v[68:71]
	v_mfma_f32_16x16x32_bf16 v[64:67], v[224:227], v[208:211], v[64:67]
	s_barrier
	s_setprio 0
	ds_read_b128 v[168:171], v143 offset:49152
	ds_read_b128 v[184:187], v143 offset:50176
	ds_read_b128 v[188:191], v143 offset:51200
	ds_read_b128 v[192:195], v143 offset:52224
	ds_read_b128 v[196:199], v143 offset:53248
	ds_read_b128 v[200:203], v143 offset:54272
	ds_read_b128 v[204:207], v143 offset:55296
	ds_read_b128 v[208:211], v143 offset:56320
	global_load_lds_dwordx4 v[152:153], off
	v_lshl_add_u64 v[152:153], v[232:233], 0, s[8:9]
	s_mov_b32 m0, s93
	s_nop 0
	global_load_lds_dwordx4 v[152:153], off
	s_setprio 1
	s_barrier
	s_waitcnt lgkmcnt(0)
	v_mfma_f32_16x16x32_bf16 v[60:63], v[144:147], v[168:171], v[60:63]
	v_mfma_f32_16x16x32_bf16 v[56:59], v[160:163], v[168:171], v[56:59]
	v_mfma_f32_16x16x32_bf16 v[52:55], v[144:147], v[188:191], v[52:55]
	v_mfma_f32_16x16x32_bf16 v[48:51], v[160:163], v[188:191], v[48:51]
	v_mfma_f32_16x16x32_bf16 v[36:39], v[144:147], v[196:199], v[36:39]
	v_mfma_f32_16x16x32_bf16 v[32:35], v[160:163], v[196:199], v[32:35]
	v_mfma_f32_16x16x32_bf16 v[20:23], v[144:147], v[204:207], v[20:23]
	v_mfma_f32_16x16x32_bf16 v[16:19], v[160:163], v[204:207], v[16:19]
	v_mfma_f32_16x16x32_bf16 v[60:63], v[148:151], v[184:187], v[60:63]
	v_mfma_f32_16x16x32_bf16 v[56:59], v[164:167], v[184:187], v[56:59]
	v_mfma_f32_16x16x32_bf16 v[52:55], v[148:151], v[192:195], v[52:55]
	v_mfma_f32_16x16x32_bf16 v[48:51], v[164:167], v[192:195], v[48:51]
	v_mfma_f32_16x16x32_bf16 v[36:39], v[148:151], v[200:203], v[36:39]
	v_mfma_f32_16x16x32_bf16 v[32:35], v[164:167], v[200:203], v[32:35]
	v_mfma_f32_16x16x32_bf16 v[20:23], v[148:151], v[208:211], v[20:23]
	v_mfma_f32_16x16x32_bf16 v[16:19], v[164:167], v[208:211], v[16:19]
	s_barrier
	s_setprio 0
	s_add_i32 s1, s17, s85
	v_lshl_add_u64 v[144:145], v[234:235], 0, s[8:9]
	s_mov_b32 m0, s1
	s_nop 0
	global_load_lds_dwordx4 v[144:145], off
	v_lshl_add_u64 v[144:145], v[236:237], 0, s[8:9]
	s_add_i32 m0, s1, 0x2000
	s_nop 0
	global_load_lds_dwordx4 v[144:145], off
	s_waitcnt vmcnt(6)
	s_setprio 1
	s_barrier
	v_mfma_f32_16x16x32_bf16 v[44:47], v[212:215], v[168:171], v[44:47]
	v_mfma_f32_16x16x32_bf16 v[40:43], v[220:223], v[168:171], v[40:43]
	v_mfma_f32_16x16x32_bf16 v[28:31], v[212:215], v[188:191], v[28:31]
	v_mfma_f32_16x16x32_bf16 v[24:27], v[220:223], v[188:191], v[24:27]
	v_mfma_f32_16x16x32_bf16 v[12:15], v[212:215], v[196:199], v[12:15]
	v_mfma_f32_16x16x32_bf16 v[8:11], v[220:223], v[196:199], v[8:11]
	s_add_u32 vcc_lo, vcc_lo, 0x100
	v_mfma_f32_16x16x32_bf16 v[4:7], v[212:215], v[204:207], v[4:7]
	s_addc_u32 vcc_hi, vcc_hi, 0
	v_mfma_f32_16x16x32_bf16 v[0:3], v[220:223], v[204:207], v[0:3]
	s_add_u32 s96, s96, 0x100
	v_mfma_f32_16x16x32_bf16 v[44:47], v[216:219], v[184:187], v[44:47]
	s_addc_u32 s65, s65, 0
	v_mfma_f32_16x16x32_bf16 v[40:43], v[224:227], v[184:187], v[40:43]
	s_cmp_ge_u32 s0, s94
	v_mfma_f32_16x16x32_bf16 v[28:31], v[216:219], v[192:195], v[28:31]
	s_mov_b32 s34, s0
	v_mfma_f32_16x16x32_bf16 v[24:27], v[224:227], v[192:195], v[24:27]
	v_mfma_f32_16x16x32_bf16 v[12:15], v[216:219], v[200:203], v[12:15]
	v_mfma_f32_16x16x32_bf16 v[8:11], v[224:227], v[200:203], v[8:11]
	v_mfma_f32_16x16x32_bf16 v[4:7], v[216:219], v[208:211], v[4:7]
	v_mfma_f32_16x16x32_bf16 v[0:3], v[224:227], v[208:211], v[0:3]
	s_barrier
	s_setprio 0
	s_cbranch_scc0 .LBB0_100

; #define PG8_STAGE(bufoff, gbase, voff) do { _Pragma("unroll") for (int _i = 0; _i < 2; ++_i) \
;         __builtin_amdgcn_global_load_lds((const unsigned*)((const char*)(gbase) + (voff)[_i]), (LAS unsigned*)(lds + (bufoff) + ldsw + _i * 8192), 16, 0, 0); } while (0)
; #define PG8_LDA(dst, b, h) do { _Pragma("unroll") for (int m = 0; m < 4; ++m) _Pragma("unroll") for (int k = 0; k < 2; ++k) dst[m][k] = *(const LAS bf16x8*)(lds + PG8_SA(b, h) + aoff + m * 2048 + k * 1024); } while (0)
; #define PG8_LDB(dst, b, h) do { _Pragma("unroll") for (int n = 0; n < 2; ++n) _Pragma("unroll") for (int k = 0; k < 2; ++k) dst[n][k] = *(const LAS bf16x8*)(lds + PG8_SB(b, h) + boff + n * 2048 + k * 1024); } while (0)
; #define PG8_MMA(ai, bj, At, Bt) do { __builtin_amdgcn_s_setprio(1); _Pragma("unroll") for (int m = 0; m < 4; ++m) _Pragma("unroll") for (int n = 0; n < 2; ++n) _Pragma("unroll") for (int k = 0; k < 2; ++k) \
;         acc[ai][bj][m][n] = __builtin_amdgcn_mfma_f32_16x16x32_bf16(Bt[n][k], At[m][k], acc[ai][bj][m][n], 0, 0, 0); __builtin_amdgcn_s_setprio(0); } while (0)
; #define PG8_WAIT_L(n) asm volatile("s_waitcnt lgkmcnt(" #n ")" ::: "memory")
; template <class Epi, class Sched>
; __device__ __forceinline__ void gemm_phase(LAS unsigned char* lds, const Gemm g, const Sched& S, const Epi& E, int tid) {
;     ...
;         const bool has_next = S.next(ui + 1, nxt);
;         const char* nA = has_next ? (const char*)g.A + (size_t)nxt.pm * tstep : cA; const char* nB = has_next ? (const char*)g.Bt + (size_t)nxt.pn * tstep : cB;
;         for (int t = 0; t < nt; t += 2) {
;             const bool last = (t == nt - 2);
;             const char* a1 = cA + (size_t)(t + 1) * kstep;
;             const char* a2 = last ? nA : cA + (size_t)(t + 2) * kstep; const char* b2 = last ? nB : cB + (size_t)(t + 2) * kstep;
;             const char* a3 = a2 + kstep; const char* b3 = b2 + kstep;
;             PG8_LDB(B0, 0, 0); PG8_SCHED; PG8_LDA(At, 0, 0); PG8_STAGE(PG8_SA(1, 1), a1 + hstep, voffA);
;             PG8_WAIT_L(8); PG8_BAR; PG8_WAIT_L(0); PG8_MMA(0, 0, At, B0); PG8_BAR; PG8_SCHED;
;             PG8_LDB(B1, 0, 1); PG8_STAGE(PG8_SB(0, 0), b2, voffB);
;             PG8_BAR; PG8_WAIT_L(0); PG8_MMA(0, 1, At, B1); PG8_BAR;
;             PG8_LDA(At, 0, 1); PG8_STAGE(PG8_SA(0, 0), a2, voffA);
;             PG8_BAR; PG8_WAIT_L(0); PG8_MMA(1, 0, At, B0); PG8_BAR; PG8_SCHED;
.LBB0_114:
	s_ashr_i32 s25, s24, 31
	s_lshl_b64 s[0:1], s[24:25], 19
	v_cmp_lt_i64_e32 vcc, s[28:29], v[158:159]
	s_add_u32 s28, s26, s0
	s_addc_u32 s29, s27, s1
	s_and_b64 s[0:1], vcc, exec
	s_cselect_b32 s25, s29, s41
	s_cselect_b32 s53, s28, s40
	s_ashr_i32 s15, s14, 31
	s_lshl_b64 s[0:1], s[14:15], 19
	s_add_u32 s30, s19, s0
	s_addc_u32 s31, s44, s1
	s_and_b64 s[0:1], vcc, exec
	s_cselect_b32 s15, s31, s43
	s_cselect_b32 s55, s30, s42
	s_add_u32 s40, s40, 0x40080
	s_addc_u32 s41, s41, 0
	s_add_u32 s58, s42, 0x100
	s_addc_u32 s60, s43, 0
	s_mov_b32 s61, -2
	s_add_u32 s0, s40, 0xfffc0080
	s_addc_u32 s1, s41, -1
	s_add_i32 s17, 0, 0x10000
	v_add_u32_e32 v160, s17, v143
	ds_read_b128 v[138:141], v160
	ds_read_b128 v[146:149], v160 offset:1024
	ds_read_b128 v[150:153], v160 offset:2048
	ds_read_b128 v[160:163], v160 offset:3072
	s_cmp_eq_u32 s61, 12
	s_cselect_b32 s43, s25, s1
	s_cselect_b32 s42, s53, s0
	s_cselect_b32 s35, s15, s60
	s_cselect_b32 s34, s55, s58
	v_lshl_add_u64 v[208:209], s[40:41], 0, v[134:135]
	s_add_i32 m0, s39, 0xc000
	ds_read_b128 v[164:167], v145
	ds_read_b128 v[184:187], v145 offset:2048
	ds_read_b128 v[192:195], v145 offset:4096
	ds_read_b128 v[200:203], v145 offset:6144
	global_load_lds_dwordx4 v[208:209], off
	v_lshl_add_u64 v[208:209], s[40:41], 0, v[136:137]
	s_add_i32 m0, s39, 0xe000
	s_nop 0
	global_load_lds_dwordx4 v[208:209], off
	s_waitcnt lgkmcnt(4)
	s_setprio 1
	s_barrier
	s_waitcnt lgkmcnt(0)
	v_mfma_f32_16x16x32_bf16 v[124:127], v[138:141], v[164:167], 0
	ds_read_b128 v[168:171], v145 offset:1024
	v_mfma_f32_16x16x32_bf16 v[120:123], v[150:153], v[164:167], 0
	ds_read_b128 v[188:191], v145 offset:3072
	v_mfma_f32_16x16x32_bf16 v[108:111], v[138:141], v[184:187], 0
	ds_read_b128 v[196:199], v145 offset:5120
	v_mfma_f32_16x16x32_bf16 v[104:107], v[150:153], v[184:187], 0
	ds_read_b128 v[204:207], v145 offset:7168
	v_mfma_f32_16x16x32_bf16 v[92:95], v[138:141], v[192:195], 0
	v_mfma_f32_16x16x32_bf16 v[88:91], v[150:153], v[192:195], 0
	v_mfma_f32_16x16x32_bf16 v[76:79], v[138:141], v[200:203], 0
	v_mfma_f32_16x16x32_bf16 v[72:75], v[150:153], v[200:203], 0
	s_waitcnt lgkmcnt(0)
	v_mfma_f32_16x16x32_bf16 v[124:127], v[146:149], v[168:171], v[124:127]
	v_mfma_f32_16x16x32_bf16 v[120:123], v[160:163], v[168:171], v[120:123]
	v_mfma_f32_16x16x32_bf16 v[108:111], v[146:149], v[188:191], v[108:111]
	v_mfma_f32_16x16x32_bf16 v[104:107], v[160:163], v[188:191], v[104:107]
	v_mfma_f32_16x16x32_bf16 v[92:95], v[146:149], v[196:199], v[92:95]
	v_mfma_f32_16x16x32_bf16 v[88:91], v[160:163], v[196:199], v[88:91]
	v_mfma_f32_16x16x32_bf16 v[76:79], v[146:149], v[204:207], v[76:79]
	v_mfma_f32_16x16x32_bf16 v[72:75], v[160:163], v[204:207], v[72:75]
	s_barrier
	s_setprio 0
	s_add_i32 s63, 0, 0x14000
	s_add_i32 s0, s17, s45
	v_add_u32_e32 v183, s63, v143
	v_lshl_add_u64 v[224:225], s[34:35], 0, v[154:155]
	s_mov_b32 m0, s0
	ds_read_b128 v[208:211], v183
	ds_read_b128 v[212:215], v183 offset:1024
	ds_read_b128 v[216:219], v183 offset:2048
	ds_read_b128 v[220:223], v183 offset:3072
	global_load_lds_dwordx4 v[224:225], off
	v_lshl_add_u64 v[226:227], s[34:35], 0, v[128:129]
	s_add_i32 m0, s0, 0x2000
	s_nop 0
	global_load_lds_dwordx4 v[226:227], off
	s_setprio 1
	s_barrier
	s_waitcnt lgkmcnt(0)
	v_mfma_f32_16x16x32_bf16 v[116:119], v[208:211], v[164:167], 0
	v_mfma_f32_16x16x32_bf16 v[112:115], v[216:219], v[164:167], 0
	v_mfma_f32_16x16x32_bf16 v[100:103], v[208:211], v[184:187], 0
	v_mfma_f32_16x16x32_bf16 v[96:99], v[216:219], v[184:187], 0
	v_mfma_f32_16x16x32_bf16 v[84:87], v[208:211], v[192:195], 0
	v_mfma_f32_16x16x32_bf16 v[80:83], v[216:219], v[192:195], 0
	s_mov_b32 m0, s39
	v_mfma_f32_16x16x32_bf16 v[68:71], v[208:211], v[200:203], 0
	v_lshl_add_u64 v[228:229], s[42:43], 0, v[132:133]
	v_mfma_f32_16x16x32_bf16 v[64:67], v[216:219], v[200:203], 0
	v_mfma_f32_16x16x32_bf16 v[116:119], v[212:215], v[168:171], v[116:119]
	v_mfma_f32_16x16x32_bf16 v[112:115], v[220:223], v[168:171], v[112:115]
	v_mfma_f32_16x16x32_bf16 v[100:103], v[212:215], v[188:191], v[100:103]
	v_mfma_f32_16x16x32_bf16 v[96:99], v[220:223], v[188:191], v[96:99]
	v_mfma_f32_16x16x32_bf16 v[84:87], v[212:215], v[196:199], v[84:87]
	v_mfma_f32_16x16x32_bf16 v[80:83], v[220:223], v[196:199], v[80:83]
	v_mfma_f32_16x16x32_bf16 v[68:71], v[212:215], v[204:207], v[68:71]
	v_mfma_f32_16x16x32_bf16 v[64:67], v[220:223], v[204:207], v[64:67]
	s_barrier
	s_setprio 0
	ds_read_b128 v[164:167], v145 offset:16384
	ds_read_b128 v[168:171], v145 offset:17408
	ds_read_b128 v[184:187], v145 offset:18432
	ds_read_b128 v[188:191], v145 offset:19456
	ds_read_b128 v[192:195], v145 offset:20480
	ds_read_b128 v[196:199], v145 offset:21504
	ds_read_b128 v[200:203], v145 offset:22528
	ds_read_b128 v[204:207], v145 offset:23552
	global_load_lds_dwordx4 v[228:229], off
	v_lshl_add_u64 v[230:231], s[42:43], 0, v[130:131]
	s_mov_b32 m0, s47
	s_nop 0
	global_load_lds_dwordx4 v[230:231], off
	s_setprio 1
	s_barrier
	s_waitcnt lgkmcnt(0)
	v_mfma_f32_16x16x32_bf16 v[60:63], v[138:141], v[164:167], 0
	v_mfma_f32_16x16x32_bf16 v[56:59], v[150:153], v[164:167], 0
	v_mfma_f32_16x16x32_bf16 v[44:47], v[138:141], v[184:187], 0
	v_mfma_f32_16x16x32_bf16 v[40:43], v[150:153], v[184:187], 0
	v_mfma_f32_16x16x32_bf16 v[28:31], v[138:141], v[192:195], 0
	v_mfma_f32_16x16x32_bf16 v[24:27], v[150:153], v[192:195], 0
	v_mfma_f32_16x16x32_bf16 v[12:15], v[138:141], v[200:203], 0
	v_mfma_f32_16x16x32_bf16 v[8:11], v[150:153], v[200:203], 0
	v_mfma_f32_16x16x32_bf16 v[60:63], v[146:149], v[168:171], v[60:63]
	v_mfma_f32_16x16x32_bf16 v[56:59], v[160:163], v[168:171], v[56:59]
	v_mfma_f32_16x16x32_bf16 v[44:47], v[146:149], v[188:191], v[44:47]
	v_mfma_f32_16x16x32_bf16 v[40:43], v[160:163], v[188:191], v[40:43]
	v_mfma_f32_16x16x32_bf16 v[28:31], v[146:149], v[196:199], v[28:31]
	v_mfma_f32_16x16x32_bf16 v[24:27], v[160:163], v[196:199], v[24:27]
	v_mfma_f32_16x16x32_bf16 v[12:15], v[146:149], v[204:207], v[12:15]
	v_mfma_f32_16x16x32_bf16 v[8:11], v[160:163], v[204:207], v[8:11]
	s_barrier
; #define PG8_STAGE(bufoff, gbase, voff) do { _Pragma("unroll") for (int _i = 0; _i < 2; ++_i) \
;         __builtin_amdgcn_global_load_lds((const unsigned*)((const char*)(gbase) + (voff)[_i]), (LAS unsigned*)(lds + (bufoff) + ldsw + _i * 8192), 16, 0, 0); } while (0)
; #define PG8_LDA(dst, b, h) do { _Pragma("unroll") for (int m = 0; m < 4; ++m) _Pragma("unroll") for (int k = 0; k < 2; ++k) dst[m][k] = *(const LAS bf16x8*)(lds + PG8_SA(b, h) + aoff + m * 2048 + k * 1024); } while (0)
; #define PG8_LDB(dst, b, h) do { _Pragma("unroll") for (int n = 0; n < 2; ++n) _Pragma("unroll") for (int k = 0; k < 2; ++k) dst[n][k] = *(const LAS bf16x8*)(lds + PG8_SB(b, h) + boff + n * 2048 + k * 1024); } while (0)
; #define PG8_MMA(ai, bj, At, Bt) do { __builtin_amdgcn_s_setprio(1); _Pragma("unroll") for (int m = 0; m < 4; ++m) _Pragma("unroll") for (int n = 0; n < 2; ++n) _Pragma("unroll") for (int k = 0; k < 2; ++k) \
;         acc[ai][bj][m][n] = __builtin_amdgcn_mfma_f32_16x16x32_bf16(Bt[n][k], At[m][k], acc[ai][bj][m][n], 0, 0, 0); __builtin_amdgcn_s_setprio(0); } while (0)
; #define PG8_WAIT_V(n) asm volatile("s_waitcnt vmcnt(" #n ")" ::: "memory")
; #define PG8_WAIT_L(n) asm volatile("s_waitcnt lgkmcnt(" #n ")" ::: "memory")
; #define PG8_BAR __builtin_amdgcn_s_barrier()
; #define PG8_SCHED __builtin_amdgcn_sched_barrier(0)
; template <class Epi, class Sched>
; __device__ __forceinline__ void gemm_phase(LAS unsigned char* lds, const Gemm g, const Sched& S, const Epi& E, int tid) {
;     ...
;             PG8_WAIT_V(6); PG8_BAR; PG8_MMA(1, 1, At, B1); PG8_BAR;
;             PG8_LDB(B0, 1, 0); PG8_SCHED; PG8_LDA(At, 1, 0); PG8_STAGE(PG8_SA(0, 1), a2 + hstep, voffA);
;             PG8_WAIT_L(8); PG8_BAR; PG8_WAIT_L(0); PG8_MMA(0, 0, At, B0); PG8_BAR; PG8_SCHED;
;             PG8_LDB(B1, 1, 1); PG8_STAGE(PG8_SB(1, 0), b3, voffB);
;             PG8_BAR; PG8_WAIT_L(0); PG8_MMA(0, 1, At, B1); PG8_BAR;
;             PG8_LDA(At, 1, 1); PG8_STAGE(PG8_SA(1, 0), a3, voffA);
;             PG8_BAR; PG8_WAIT_L(0); PG8_MMA(1, 0, At, B0); PG8_BAR; PG8_SCHED;
	s_setprio 0
	s_add_u32 s0, s34, 0x40000
	s_addc_u32 s1, s35, 0
	s_add_i32 s17, s63, s45
	v_lshl_add_u64 v[138:139], s[0:1], 0, v[154:155]
	s_mov_b32 m0, s17
	s_nop 0
	global_load_lds_dwordx4 v[138:139], off
	v_lshl_add_u64 v[138:139], s[0:1], 0, v[128:129]
	s_add_i32 m0, s17, 0x2000
	s_nop 0
	global_load_lds_dwordx4 v[138:139], off
	s_waitcnt vmcnt(16)
	s_setprio 1
	s_barrier
	v_mfma_f32_16x16x32_bf16 v[52:55], v[208:211], v[164:167], 0
	v_mfma_f32_16x16x32_bf16 v[48:51], v[216:219], v[164:167], 0
	v_mfma_f32_16x16x32_bf16 v[36:39], v[208:211], v[184:187], 0
	v_mfma_f32_16x16x32_bf16 v[32:35], v[216:219], v[184:187], 0
	v_mfma_f32_16x16x32_bf16 v[20:23], v[208:211], v[192:195], 0
	v_mfma_f32_16x16x32_bf16 v[16:19], v[216:219], v[192:195], 0
	s_add_i32 s17, 0, 0x18000
	v_mfma_f32_16x16x32_bf16 v[4:7], v[208:211], v[200:203], 0
	v_add_u32_e32 v160, s17, v143
	v_mfma_f32_16x16x32_bf16 v[0:3], v[216:219], v[200:203], 0
	v_mfma_f32_16x16x32_bf16 v[52:55], v[212:215], v[168:171], v[52:55]
	v_mfma_f32_16x16x32_bf16 v[48:51], v[220:223], v[168:171], v[48:51]
	v_mfma_f32_16x16x32_bf16 v[36:39], v[212:215], v[188:191], v[36:39]
	v_mfma_f32_16x16x32_bf16 v[32:35], v[220:223], v[188:191], v[32:35]
	v_mfma_f32_16x16x32_bf16 v[20:23], v[212:215], v[196:199], v[20:23]
	v_mfma_f32_16x16x32_bf16 v[16:19], v[220:223], v[196:199], v[16:19]
	v_mfma_f32_16x16x32_bf16 v[4:7], v[212:215], v[204:207], v[4:7]
	v_mfma_f32_16x16x32_bf16 v[0:3], v[220:223], v[204:207], v[0:3]
	s_barrier
	s_setprio 0
	ds_read_b128 v[138:141], v160
	ds_read_b128 v[146:149], v160 offset:1024
	ds_read_b128 v[150:153], v160 offset:2048
	ds_read_b128 v[160:163], v160 offset:3072
	s_add_u32 s0, s42, 0x40000
	s_addc_u32 s1, s43, 0
	s_mov_b32 m0, s48
	v_lshl_add_u64 v[208:209], s[0:1], 0, v[132:133]
	ds_read_b128 v[164:167], v145 offset:32768
	ds_read_b128 v[184:187], v145 offset:34816
	ds_read_b128 v[192:195], v145 offset:36864
	ds_read_b128 v[200:203], v145 offset:38912
	global_load_lds_dwordx4 v[208:209], off
	v_lshl_add_u64 v[208:209], s[0:1], 0, v[130:131]
	s_mov_b32 m0, s49
	s_nop 0
	global_load_lds_dwordx4 v[208:209], off
	s_waitcnt lgkmcnt(4)
	s_setprio 1
	s_barrier
	s_waitcnt lgkmcnt(0)
	v_mfma_f32_16x16x32_bf16 v[124:127], v[138:141], v[164:167], v[124:127]
	ds_read_b128 v[168:171], v145 offset:33792
	v_mfma_f32_16x16x32_bf16 v[120:123], v[150:153], v[164:167], v[120:123]
	ds_read_b128 v[188:191], v145 offset:35840
	v_mfma_f32_16x16x32_bf16 v[108:111], v[138:141], v[184:187], v[108:111]
	ds_read_b128 v[196:199], v145 offset:37888
	v_mfma_f32_16x16x32_bf16 v[104:107], v[150:153], v[184:187], v[104:107]
	ds_read_b128 v[204:207], v145 offset:39936
	v_mfma_f32_16x16x32_bf16 v[92:95], v[138:141], v[192:195], v[92:95]
	v_mfma_f32_16x16x32_bf16 v[88:91], v[150:153], v[192:195], v[88:91]
	v_mfma_f32_16x16x32_bf16 v[76:79], v[138:141], v[200:203], v[76:79]
	v_mfma_f32_16x16x32_bf16 v[72:75], v[150:153], v[200:203], v[72:75]
	s_waitcnt lgkmcnt(0)
	v_mfma_f32_16x16x32_bf16 v[124:127], v[146:149], v[168:171], v[124:127]
	v_mfma_f32_16x16x32_bf16 v[120:123], v[160:163], v[168:171], v[120:123]
	v_mfma_f32_16x16x32_bf16 v[108:111], v[146:149], v[188:191], v[108:111]
	v_mfma_f32_16x16x32_bf16 v[104:107], v[160:163], v[188:191], v[104:107]
	v_mfma_f32_16x16x32_bf16 v[92:95], v[146:149], v[196:199], v[92:95]
	v_mfma_f32_16x16x32_bf16 v[88:91], v[160:163], v[196:199], v[88:91]
	v_mfma_f32_16x16x32_bf16 v[76:79], v[146:149], v[204:207], v[76:79]
	v_mfma_f32_16x16x32_bf16 v[72:75], v[160:163], v[204:207], v[72:75]
	s_barrier
	s_setprio 0
	s_add_i32 s42, 0, 0x1c000
	s_add_i32 s0, s17, s45
	v_add_u32_e32 v183, s42, v143
	v_lshl_add_u64 v[224:225], v[224:225], 0, s[8:9]
	s_mov_b32 m0, s0
	ds_read_b128 v[208:211], v183
	ds_read_b128 v[212:215], v183 offset:1024
	ds_read_b128 v[216:219], v183 offset:2048
	ds_read_b128 v[220:223], v183 offset:3072
	global_load_lds_dwordx4 v[224:225], off
	v_lshl_add_u64 v[224:225], v[226:227], 0, s[8:9]
	s_add_i32 m0, s0, 0x2000
	s_nop 0
	global_load_lds_dwordx4 v[224:225], off
	s_waitcnt vmcnt(10)
	s_setprio 1
	s_barrier
	s_waitcnt lgkmcnt(0)
	v_mfma_f32_16x16x32_bf16 v[116:119], v[208:211], v[164:167], v[116:119]
	v_mfma_f32_16x16x32_bf16 v[112:115], v[216:219], v[164:167], v[112:115]
	v_mfma_f32_16x16x32_bf16 v[100:103], v[208:211], v[184:187], v[100:103]
	v_mfma_f32_16x16x32_bf16 v[96:99], v[216:219], v[184:187], v[96:99]
	v_mfma_f32_16x16x32_bf16 v[84:87], v[208:211], v[192:195], v[84:87]
	v_mfma_f32_16x16x32_bf16 v[80:83], v[216:219], v[192:195], v[80:83]
	s_mov_b32 m0, s6
	v_mfma_f32_16x16x32_bf16 v[68:71], v[208:211], v[200:203], v[68:71]
	v_lshl_add_u64 v[224:225], v[228:229], 0, s[8:9]
	v_mfma_f32_16x16x32_bf16 v[64:67], v[216:219], v[200:203], v[64:67]
	v_mfma_f32_16x16x32_bf16 v[116:119], v[212:215], v[168:171], v[116:119]
	v_mfma_f32_16x16x32_bf16 v[112:115], v[220:223], v[168:171], v[112:115]
	v_mfma_f32_16x16x32_bf16 v[100:103], v[212:215], v[188:191], v[100:103]
	v_mfma_f32_16x16x32_bf16 v[96:99], v[220:223], v[188:191], v[96:99]
	v_mfma_f32_16x16x32_bf16 v[84:87], v[212:215], v[196:199], v[84:87]
	v_mfma_f32_16x16x32_bf16 v[80:83], v[220:223], v[196:199], v[80:83]
	v_mfma_f32_16x16x32_bf16 v[68:71], v[212:215], v[204:207], v[68:71]
	v_mfma_f32_16x16x32_bf16 v[64:67], v[220:223], v[204:207], v[64:67]
	s_barrier
	s_setprio 0
	ds_read_b128 v[164:167], v145 offset:49152
	ds_read_b128 v[168:171], v145 offset:50176
	ds_read_b128 v[184:187], v145 offset:51200
	ds_read_b128 v[188:191], v145 offset:52224
	ds_read_b128 v[192:195], v145 offset:53248
	ds_read_b128 v[196:199], v145 offset:54272
	ds_read_b128 v[200:203], v145 offset:55296
	ds_read_b128 v[204:207], v145 offset:56320
	global_load_lds_dwordx4 v[224:225], off
	v_lshl_add_u64 v[224:225], v[230:231], 0, s[8:9]
	s_mov_b32 m0, s50
	s_nop 0
	global_load_lds_dwordx4 v[224:225], off
	s_setprio 1
	s_barrier
; #define PG8_STAGE(bufoff, gbase, voff) do { _Pragma("unroll") for (int _i = 0; _i < 2; ++_i) \
;         __builtin_amdgcn_global_load_lds((const unsigned*)((const char*)(gbase) + (voff)[_i]), (LAS unsigned*)(lds + (bufoff) + ldsw + _i * 8192), 16, 0, 0); } while (0)
; #define PG8_LDA(dst, b, h) do { _Pragma("unroll") for (int m = 0; m < 4; ++m) _Pragma("unroll") for (int k = 0; k < 2; ++k) dst[m][k] = *(const LAS bf16x8*)(lds + PG8_SA(b, h) + aoff + m * 2048 + k * 1024); } while (0)
; #define PG8_LDB(dst, b, h) do { _Pragma("unroll") for (int n = 0; n < 2; ++n) _Pragma("unroll") for (int k = 0; k < 2; ++k) dst[n][k] = *(const LAS bf16x8*)(lds + PG8_SB(b, h) + boff + n * 2048 + k * 1024); } while (0)
; #define PG8_MMA(ai, bj, At, Bt) do { __builtin_amdgcn_s_setprio(1); _Pragma("unroll") for (int m = 0; m < 4; ++m) _Pragma("unroll") for (int n = 0; n < 2; ++n) _Pragma("unroll") for (int k = 0; k < 2; ++k) \
;         acc[ai][bj][m][n] = __builtin_amdgcn_mfma_f32_16x16x32_bf16(Bt[n][k], At[m][k], acc[ai][bj][m][n], 0, 0, 0); __builtin_amdgcn_s_setprio(0); } while (0)
; #define PG8_WAIT_V(n) asm volatile("s_waitcnt vmcnt(" #n ")" ::: "memory")
; #define PG8_WAIT_L(n) asm volatile("s_waitcnt lgkmcnt(" #n ")" ::: "memory")
; #define PG8_BAR __builtin_amdgcn_s_barrier()
; #define PG8_SCHED __builtin_amdgcn_sched_barrier(0)
; template <class Epi, class Sched>
; __device__ __forceinline__ void gemm_phase(LAS unsigned char* lds, const Gemm g, const Sched& S, const Epi& E, int tid) {
;     ...
;         for (int t = 0; t < nt; t += 2) {
;             const bool last = (t == nt - 2);
;             const char* a1 = cA + (size_t)(t + 1) * kstep;
;             const char* a2 = last ? nA : cA + (size_t)(t + 2) * kstep; const char* b2 = last ? nB : cB + (size_t)(t + 2) * kstep;
;             const char* a3 = a2 + kstep; const char* b3 = b2 + kstep;
;             PG8_LDB(B0, 0, 0); PG8_SCHED; PG8_LDA(At, 0, 0); PG8_STAGE(PG8_SA(1, 1), a1 + hstep, voffA);
;             PG8_WAIT_L(8); PG8_BAR; PG8_WAIT_L(0); PG8_MMA(0, 0, At, B0); PG8_BAR; PG8_SCHED;
;             PG8_LDB(B1, 0, 1); PG8_STAGE(PG8_SB(0, 0), b2, voffB);
;     ...
;             PG8_BAR; PG8_WAIT_L(0); PG8_MMA(1, 0, At, B0); PG8_BAR; PG8_SCHED;
;             PG8_STAGE(PG8_SB(1, 1), b3 + hstep, voffB);
;             PG8_WAIT_V(6); PG8_BAR; PG8_MMA(1, 1, At, B1); PG8_BAR;
	s_waitcnt lgkmcnt(0)
	v_mfma_f32_16x16x32_bf16 v[60:63], v[138:141], v[164:167], v[60:63]
	v_mfma_f32_16x16x32_bf16 v[56:59], v[150:153], v[164:167], v[56:59]
	v_mfma_f32_16x16x32_bf16 v[44:47], v[138:141], v[184:187], v[44:47]
	v_mfma_f32_16x16x32_bf16 v[40:43], v[150:153], v[184:187], v[40:43]
	v_mfma_f32_16x16x32_bf16 v[28:31], v[138:141], v[192:195], v[28:31]
	v_mfma_f32_16x16x32_bf16 v[24:27], v[150:153], v[192:195], v[24:27]
	v_mfma_f32_16x16x32_bf16 v[12:15], v[138:141], v[200:203], v[12:15]
	v_mfma_f32_16x16x32_bf16 v[8:11], v[150:153], v[200:203], v[8:11]
	v_mfma_f32_16x16x32_bf16 v[60:63], v[146:149], v[168:171], v[60:63]
	v_mfma_f32_16x16x32_bf16 v[56:59], v[160:163], v[168:171], v[56:59]
	v_mfma_f32_16x16x32_bf16 v[44:47], v[146:149], v[188:191], v[44:47]
	v_mfma_f32_16x16x32_bf16 v[40:43], v[160:163], v[188:191], v[40:43]
	v_mfma_f32_16x16x32_bf16 v[28:31], v[146:149], v[196:199], v[28:31]
	v_mfma_f32_16x16x32_bf16 v[24:27], v[160:163], v[196:199], v[24:27]
	v_mfma_f32_16x16x32_bf16 v[12:15], v[146:149], v[204:207], v[12:15]
	v_mfma_f32_16x16x32_bf16 v[8:11], v[160:163], v[204:207], v[8:11]
	s_barrier
	s_setprio 0
	s_add_u32 s0, s34, 0x40080
	s_addc_u32 s1, s35, 0
	s_add_i32 s17, s42, s45
	v_lshl_add_u64 v[138:139], s[0:1], 0, v[154:155]
	s_mov_b32 m0, s17
	s_nop 0
	global_load_lds_dwordx4 v[138:139], off
	v_lshl_add_u64 v[138:139], s[0:1], 0, v[128:129]
	s_add_i32 m0, s17, 0x2000
	s_nop 0
	global_load_lds_dwordx4 v[138:139], off
	s_waitcnt vmcnt(6)
	s_setprio 1
	s_barrier
	v_mfma_f32_16x16x32_bf16 v[52:55], v[208:211], v[164:167], v[52:55]
	v_mfma_f32_16x16x32_bf16 v[48:51], v[216:219], v[164:167], v[48:51]
	v_mfma_f32_16x16x32_bf16 v[36:39], v[208:211], v[184:187], v[36:39]
	v_mfma_f32_16x16x32_bf16 v[32:35], v[216:219], v[184:187], v[32:35]
	v_mfma_f32_16x16x32_bf16 v[20:23], v[208:211], v[192:195], v[20:23]
	v_mfma_f32_16x16x32_bf16 v[16:19], v[216:219], v[192:195], v[16:19]
	s_add_i32 s61, s61, 2
	v_mfma_f32_16x16x32_bf16 v[4:7], v[208:211], v[200:203], v[4:7]
	s_add_u32 s40, s40, 0x100
	v_mfma_f32_16x16x32_bf16 v[0:3], v[216:219], v[200:203], v[0:3]
	s_addc_u32 s41, s41, 0
	v_mfma_f32_16x16x32_bf16 v[52:55], v[212:215], v[168:171], v[52:55]
	s_add_u32 s58, s58, 0x100
	v_mfma_f32_16x16x32_bf16 v[48:51], v[220:223], v[168:171], v[48:51]
	s_addc_u32 s60, s60, 0
	v_mfma_f32_16x16x32_bf16 v[36:39], v[212:215], v[188:191], v[36:39]
	s_cmp_gt_u32 s61, 13
	v_mfma_f32_16x16x32_bf16 v[32:35], v[220:223], v[188:191], v[32:35]
	v_mfma_f32_16x16x32_bf16 v[20:23], v[212:215], v[196:199], v[20:23]
	v_mfma_f32_16x16x32_bf16 v[16:19], v[220:223], v[196:199], v[16:19]
	v_mfma_f32_16x16x32_bf16 v[4:7], v[212:215], v[204:207], v[4:7]
	v_mfma_f32_16x16x32_bf16 v[0:3], v[220:223], v[204:207], v[0:3]
	s_barrier
	s_setprio 0
	s_cbranch_scc1 .Lpeel_exit_swiglu
.LBB0_115:
	s_add_u32 s0, s40, 0xfffc0080
	s_addc_u32 s1, s41, -1
	s_add_i32 s17, 0, 0x10000
	v_add_u32_e32 v160, s17, v143
	ds_read_b128 v[138:141], v160
	ds_read_b128 v[146:149], v160 offset:1024
	ds_read_b128 v[150:153], v160 offset:2048
	ds_read_b128 v[160:163], v160 offset:3072
	s_cmp_eq_u32 s61, 12
	s_cselect_b32 s43, s25, s1
	s_cselect_b32 s42, s53, s0
	s_cselect_b32 s35, s15, s60
	s_cselect_b32 s34, s55, s58
	v_lshl_add_u64 v[208:209], s[40:41], 0, v[134:135]
	s_add_i32 m0, s39, 0xc000
	ds_read_b128 v[164:167], v145
	ds_read_b128 v[184:187], v145 offset:2048
	ds_read_b128 v[192:195], v145 offset:4096
	ds_read_b128 v[200:203], v145 offset:6144
	global_load_lds_dwordx4 v[208:209], off
	v_lshl_add_u64 v[208:209], s[40:41], 0, v[136:137]
	s_add_i32 m0, s39, 0xe000
	s_nop 0
	global_load_lds_dwordx4 v[208:209], off
	s_waitcnt lgkmcnt(4)
	s_setprio 1
	s_barrier
	s_waitcnt lgkmcnt(0)
	v_mfma_f32_16x16x32_bf16 v[124:127], v[138:141], v[164:167], v[124:127]
	ds_read_b128 v[168:171], v145 offset:1024
	v_mfma_f32_16x16x32_bf16 v[120:123], v[150:153], v[164:167], v[120:123]
	ds_read_b128 v[188:191], v145 offset:3072
	v_mfma_f32_16x16x32_bf16 v[108:111], v[138:141], v[184:187], v[108:111]
	ds_read_b128 v[196:199], v145 offset:5120
	v_mfma_f32_16x16x32_bf16 v[104:107], v[150:153], v[184:187], v[104:107]
	ds_read_b128 v[204:207], v145 offset:7168
	v_mfma_f32_16x16x32_bf16 v[92:95], v[138:141], v[192:195], v[92:95]
	v_mfma_f32_16x16x32_bf16 v[88:91], v[150:153], v[192:195], v[88:91]
	v_mfma_f32_16x16x32_bf16 v[76:79], v[138:141], v[200:203], v[76:79]
	v_mfma_f32_16x16x32_bf16 v[72:75], v[150:153], v[200:203], v[72:75]
	s_waitcnt lgkmcnt(0)
	v_mfma_f32_16x16x32_bf16 v[124:127], v[146:149], v[168:171], v[124:127]
	v_mfma_f32_16x16x32_bf16 v[120:123], v[160:163], v[168:171], v[120:123]
	v_mfma_f32_16x16x32_bf16 v[108:111], v[146:149], v[188:191], v[108:111]
	v_mfma_f32_16x16x32_bf16 v[104:107], v[160:163], v[188:191], v[104:107]
	v_mfma_f32_16x16x32_bf16 v[92:95], v[146:149], v[196:199], v[92:95]
	v_mfma_f32_16x16x32_bf16 v[88:91], v[160:163], v[196:199], v[88:91]
	v_mfma_f32_16x16x32_bf16 v[76:79], v[146:149], v[204:207], v[76:79]
	v_mfma_f32_16x16x32_bf16 v[72:75], v[160:163], v[204:207], v[72:75]
	s_barrier
	s_setprio 0
	s_add_i32 s63, 0, 0x14000
	s_add_i32 s0, s17, s45
	v_add_u32_e32 v183, s63, v143
	v_lshl_add_u64 v[224:225], s[34:35], 0, v[154:155]
	s_mov_b32 m0, s0
	ds_read_b128 v[208:211], v183
	ds_read_b128 v[212:215], v183 offset:1024
	ds_read_b128 v[216:219], v183 offset:2048
	ds_read_b128 v[220:223], v183 offset:3072
	global_load_lds_dwordx4 v[224:225], off
	v_lshl_add_u64 v[226:227], s[34:35], 0, v[128:129]
	s_add_i32 m0, s0, 0x2000
	s_nop 0
	global_load_lds_dwordx4 v[226:227], off
	s_setprio 1
	s_barrier
; #define PG8_STAGE(bufoff, gbase, voff) do { _Pragma("unroll") for (int _i = 0; _i < 2; ++_i) \
;         __builtin_amdgcn_global_load_lds((const unsigned*)((const char*)(gbase) + (voff)[_i]), (LAS unsigned*)(lds + (bufoff) + ldsw + _i * 8192), 16, 0, 0); } while (0)
; #define PG8_LDA(dst, b, h) do { _Pragma("unroll") for (int m = 0; m < 4; ++m) _Pragma("unroll") for (int k = 0; k < 2; ++k) dst[m][k] = *(const LAS bf16x8*)(lds + PG8_SA(b, h) + aoff + m * 2048 + k * 1024); } while (0)
; #define PG8_LDB(dst, b, h) do { _Pragma("unroll") for (int n = 0; n < 2; ++n) _Pragma("unroll") for (int k = 0; k < 2; ++k) dst[n][k] = *(const LAS bf16x8*)(lds + PG8_SB(b, h) + boff + n * 2048 + k * 1024); } while (0)
; #define PG8_MMA(ai, bj, At, Bt) do { __builtin_amdgcn_s_setprio(1); _Pragma("unroll") for (int m = 0; m < 4; ++m) _Pragma("unroll") for (int n = 0; n < 2; ++n) _Pragma("unroll") for (int k = 0; k < 2; ++k) \
;         acc[ai][bj][m][n] = __builtin_amdgcn_mfma_f32_16x16x32_bf16(Bt[n][k], At[m][k], acc[ai][bj][m][n], 0, 0, 0); __builtin_amdgcn_s_setprio(0); } while (0)
; #define PG8_WAIT_V(n) asm volatile("s_waitcnt vmcnt(" #n ")" ::: "memory")
; #define PG8_WAIT_L(n) asm volatile("s_waitcnt lgkmcnt(" #n ")" ::: "memory")
; #define PG8_BAR __builtin_amdgcn_s_barrier()
; #define PG8_SCHED __builtin_amdgcn_sched_barrier(0)
; template <class Epi, class Sched>
; __device__ __forceinline__ void gemm_phase(LAS unsigned char* lds, const Gemm g, const Sched& S, const Epi& E, int tid) {
;     ...
;             PG8_BAR; PG8_WAIT_L(0); PG8_MMA(0, 1, At, B1); PG8_BAR;
;             PG8_LDA(At, 0, 1); PG8_STAGE(PG8_SA(0, 0), a2, voffA);
;             PG8_BAR; PG8_WAIT_L(0); PG8_MMA(1, 0, At, B0); PG8_BAR; PG8_SCHED;
;             PG8_STAGE(PG8_SB(0, 1), b2 + hstep, voffB);
;             PG8_WAIT_V(6); PG8_BAR; PG8_MMA(1, 1, At, B1); PG8_BAR;
;             PG8_LDB(B0, 1, 0); PG8_SCHED; PG8_LDA(At, 1, 0); PG8_STAGE(PG8_SA(0, 1), a2 + hstep, voffA);
	s_waitcnt lgkmcnt(0)
	v_mfma_f32_16x16x32_bf16 v[116:119], v[208:211], v[164:167], v[116:119]
	v_mfma_f32_16x16x32_bf16 v[112:115], v[216:219], v[164:167], v[112:115]
	v_mfma_f32_16x16x32_bf16 v[100:103], v[208:211], v[184:187], v[100:103]
	v_mfma_f32_16x16x32_bf16 v[96:99], v[216:219], v[184:187], v[96:99]
	v_mfma_f32_16x16x32_bf16 v[84:87], v[208:211], v[192:195], v[84:87]
	v_mfma_f32_16x16x32_bf16 v[80:83], v[216:219], v[192:195], v[80:83]
	s_mov_b32 m0, s39
	v_mfma_f32_16x16x32_bf16 v[68:71], v[208:211], v[200:203], v[68:71]
	v_lshl_add_u64 v[228:229], s[42:43], 0, v[132:133]
	v_mfma_f32_16x16x32_bf16 v[64:67], v[216:219], v[200:203], v[64:67]
	v_mfma_f32_16x16x32_bf16 v[116:119], v[212:215], v[168:171], v[116:119]
	v_mfma_f32_16x16x32_bf16 v[112:115], v[220:223], v[168:171], v[112:115]
	v_mfma_f32_16x16x32_bf16 v[100:103], v[212:215], v[188:191], v[100:103]
	v_mfma_f32_16x16x32_bf16 v[96:99], v[220:223], v[188:191], v[96:99]
	v_mfma_f32_16x16x32_bf16 v[84:87], v[212:215], v[196:199], v[84:87]
	v_mfma_f32_16x16x32_bf16 v[80:83], v[220:223], v[196:199], v[80:83]
	v_mfma_f32_16x16x32_bf16 v[68:71], v[212:215], v[204:207], v[68:71]
	v_mfma_f32_16x16x32_bf16 v[64:67], v[220:223], v[204:207], v[64:67]
	s_barrier
	s_setprio 0
	ds_read_b128 v[164:167], v145 offset:16384
	ds_read_b128 v[168:171], v145 offset:17408
	ds_read_b128 v[184:187], v145 offset:18432
	ds_read_b128 v[188:191], v145 offset:19456
	ds_read_b128 v[192:195], v145 offset:20480
	ds_read_b128 v[196:199], v145 offset:21504
	ds_read_b128 v[200:203], v145 offset:22528
	ds_read_b128 v[204:207], v145 offset:23552
	global_load_lds_dwordx4 v[228:229], off
	v_lshl_add_u64 v[230:231], s[42:43], 0, v[130:131]
	s_mov_b32 m0, s47
	s_nop 0
	global_load_lds_dwordx4 v[230:231], off
	s_setprio 1
	s_barrier
	s_waitcnt lgkmcnt(0)
	v_mfma_f32_16x16x32_bf16 v[60:63], v[138:141], v[164:167], v[60:63]
	v_mfma_f32_16x16x32_bf16 v[56:59], v[150:153], v[164:167], v[56:59]
	v_mfma_f32_16x16x32_bf16 v[44:47], v[138:141], v[184:187], v[44:47]
	v_mfma_f32_16x16x32_bf16 v[40:43], v[150:153], v[184:187], v[40:43]
	v_mfma_f32_16x16x32_bf16 v[28:31], v[138:141], v[192:195], v[28:31]
	v_mfma_f32_16x16x32_bf16 v[24:27], v[150:153], v[192:195], v[24:27]
	v_mfma_f32_16x16x32_bf16 v[12:15], v[138:141], v[200:203], v[12:15]
	v_mfma_f32_16x16x32_bf16 v[8:11], v[150:153], v[200:203], v[8:11]
	v_mfma_f32_16x16x32_bf16 v[60:63], v[146:149], v[168:171], v[60:63]
	v_mfma_f32_16x16x32_bf16 v[56:59], v[160:163], v[168:171], v[56:59]
	v_mfma_f32_16x16x32_bf16 v[44:47], v[146:149], v[188:191], v[44:47]
	v_mfma_f32_16x16x32_bf16 v[40:43], v[160:163], v[188:191], v[40:43]
	v_mfma_f32_16x16x32_bf16 v[28:31], v[146:149], v[196:199], v[28:31]
	v_mfma_f32_16x16x32_bf16 v[24:27], v[160:163], v[196:199], v[24:27]
	v_mfma_f32_16x16x32_bf16 v[12:15], v[146:149], v[204:207], v[12:15]
	v_mfma_f32_16x16x32_bf16 v[8:11], v[160:163], v[204:207], v[8:11]
	s_barrier
	s_setprio 0
	s_add_u32 s0, s34, 0x40000
	s_addc_u32 s1, s35, 0
	s_add_i32 s17, s63, s45
	v_lshl_add_u64 v[138:139], s[0:1], 0, v[154:155]
	s_mov_b32 m0, s17
	s_nop 0
	global_load_lds_dwordx4 v[138:139], off
	v_lshl_add_u64 v[138:139], s[0:1], 0, v[128:129]
	s_add_i32 m0, s17, 0x2000
	s_nop 0
	global_load_lds_dwordx4 v[138:139], off
	s_waitcnt vmcnt(6)
	s_setprio 1
	s_barrier
	v_mfma_f32_16x16x32_bf16 v[52:55], v[208:211], v[164:167], v[52:55]
	v_mfma_f32_16x16x32_bf16 v[48:51], v[216:219], v[164:167], v[48:51]
	v_mfma_f32_16x16x32_bf16 v[36:39], v[208:211], v[184:187], v[36:39]
	v_mfma_f32_16x16x32_bf16 v[32:35], v[216:219], v[184:187], v[32:35]
	v_mfma_f32_16x16x32_bf16 v[20:23], v[208:211], v[192:195], v[20:23]
	v_mfma_f32_16x16x32_bf16 v[16:19], v[216:219], v[192:195], v[16:19]
	s_add_i32 s17, 0, 0x18000
	v_mfma_f32_16x16x32_bf16 v[4:7], v[208:211], v[200:203], v[4:7]
	v_add_u32_e32 v160, s17, v143
	v_mfma_f32_16x16x32_bf16 v[0:3], v[216:219], v[200:203], v[0:3]
	v_mfma_f32_16x16x32_bf16 v[52:55], v[212:215], v[168:171], v[52:55]
	v_mfma_f32_16x16x32_bf16 v[48:51], v[220:223], v[168:171], v[48:51]
	v_mfma_f32_16x16x32_bf16 v[36:39], v[212:215], v[188:191], v[36:39]
	v_mfma_f32_16x16x32_bf16 v[32:35], v[220:223], v[188:191], v[32:35]
	v_mfma_f32_16x16x32_bf16 v[20:23], v[212:215], v[196:199], v[20:23]
	v_mfma_f32_16x16x32_bf16 v[16:19], v[220:223], v[196:199], v[16:19]
	v_mfma_f32_16x16x32_bf16 v[4:7], v[212:215], v[204:207], v[4:7]
	v_mfma_f32_16x16x32_bf16 v[0:3], v[220:223], v[204:207], v[0:3]
	s_barrier
	s_setprio 0
	ds_read_b128 v[138:141], v160
	ds_read_b128 v[146:149], v160 offset:1024
	ds_read_b128 v[150:153], v160 offset:2048
	ds_read_b128 v[160:163], v160 offset:3072
	s_add_u32 s0, s42, 0x40000
	s_addc_u32 s1, s43, 0
	s_mov_b32 m0, s48
	v_lshl_add_u64 v[208:209], s[0:1], 0, v[132:133]
	ds_read_b128 v[164:167], v145 offset:32768
	ds_read_b128 v[184:187], v145 offset:34816
	ds_read_b128 v[192:195], v145 offset:36864
	ds_read_b128 v[200:203], v145 offset:38912
	global_load_lds_dwordx4 v[208:209], off
	v_lshl_add_u64 v[208:209], s[0:1], 0, v[130:131]
	s_mov_b32 m0, s49
	s_nop 0
	global_load_lds_dwordx4 v[208:209], off
	s_waitcnt lgkmcnt(4)
	s_setprio 1
	s_barrier
; #define PG8_STAGE(bufoff, gbase, voff) do { _Pragma("unroll") for (int _i = 0; _i < 2; ++_i) \
;         __builtin_amdgcn_global_load_lds((const unsigned*)((const char*)(gbase) + (voff)[_i]), (LAS unsigned*)(lds + (bufoff) + ldsw + _i * 8192), 16, 0, 0); } while (0)
; #define PG8_LDA(dst, b, h) do { _Pragma("unroll") for (int m = 0; m < 4; ++m) _Pragma("unroll") for (int k = 0; k < 2; ++k) dst[m][k] = *(const LAS bf16x8*)(lds + PG8_SA(b, h) + aoff + m * 2048 + k * 1024); } while (0)
; #define PG8_LDB(dst, b, h) do { _Pragma("unroll") for (int n = 0; n < 2; ++n) _Pragma("unroll") for (int k = 0; k < 2; ++k) dst[n][k] = *(const LAS bf16x8*)(lds + PG8_SB(b, h) + boff + n * 2048 + k * 1024); } while (0)
; #define PG8_MMA(ai, bj, At, Bt) do { __builtin_amdgcn_s_setprio(1); _Pragma("unroll") for (int m = 0; m < 4; ++m) _Pragma("unroll") for (int n = 0; n < 2; ++n) _Pragma("unroll") for (int k = 0; k < 2; ++k) \
;         acc[ai][bj][m][n] = __builtin_amdgcn_mfma_f32_16x16x32_bf16(Bt[n][k], At[m][k], acc[ai][bj][m][n], 0, 0, 0); __builtin_amdgcn_s_setprio(0); } while (0)
; #define PG8_WAIT_V(n) asm volatile("s_waitcnt vmcnt(" #n ")" ::: "memory")
; #define PG8_WAIT_L(n) asm volatile("s_waitcnt lgkmcnt(" #n ")" ::: "memory")
; #define PG8_BAR __builtin_amdgcn_s_barrier()
; #define PG8_SCHED __builtin_amdgcn_sched_barrier(0)
; template <class Epi, class Sched>
; __device__ __forceinline__ void gemm_phase(LAS unsigned char* lds, const Gemm g, const Sched& S, const Epi& E, int tid) {
;     ...
;             PG8_WAIT_L(8); PG8_BAR; PG8_WAIT_L(0); PG8_MMA(0, 0, At, B0); PG8_BAR; PG8_SCHED;
;             PG8_LDB(B1, 1, 1); PG8_STAGE(PG8_SB(1, 0), b3, voffB);
;             PG8_BAR; PG8_WAIT_L(0); PG8_MMA(0, 1, At, B1); PG8_BAR;
;             PG8_LDA(At, 1, 1); PG8_STAGE(PG8_SA(1, 0), a3, voffA);
;             PG8_BAR; PG8_WAIT_L(0); PG8_MMA(1, 0, At, B0); PG8_BAR; PG8_SCHED;
;             PG8_STAGE(PG8_SB(1, 1), b3 + hstep, voffB);
;             PG8_WAIT_V(6); PG8_BAR; PG8_MMA(1, 1, At, B1); PG8_BAR;
	s_waitcnt lgkmcnt(0)
	v_mfma_f32_16x16x32_bf16 v[124:127], v[138:141], v[164:167], v[124:127]
	ds_read_b128 v[168:171], v145 offset:33792
	v_mfma_f32_16x16x32_bf16 v[120:123], v[150:153], v[164:167], v[120:123]
	ds_read_b128 v[188:191], v145 offset:35840
	v_mfma_f32_16x16x32_bf16 v[108:111], v[138:141], v[184:187], v[108:111]
	ds_read_b128 v[196:199], v145 offset:37888
	v_mfma_f32_16x16x32_bf16 v[104:107], v[150:153], v[184:187], v[104:107]
	ds_read_b128 v[204:207], v145 offset:39936
	v_mfma_f32_16x16x32_bf16 v[92:95], v[138:141], v[192:195], v[92:95]
	v_mfma_f32_16x16x32_bf16 v[88:91], v[150:153], v[192:195], v[88:91]
	v_mfma_f32_16x16x32_bf16 v[76:79], v[138:141], v[200:203], v[76:79]
	v_mfma_f32_16x16x32_bf16 v[72:75], v[150:153], v[200:203], v[72:75]
	s_waitcnt lgkmcnt(0)
	v_mfma_f32_16x16x32_bf16 v[124:127], v[146:149], v[168:171], v[124:127]
	v_mfma_f32_16x16x32_bf16 v[120:123], v[160:163], v[168:171], v[120:123]
	v_mfma_f32_16x16x32_bf16 v[108:111], v[146:149], v[188:191], v[108:111]
	v_mfma_f32_16x16x32_bf16 v[104:107], v[160:163], v[188:191], v[104:107]
	v_mfma_f32_16x16x32_bf16 v[92:95], v[146:149], v[196:199], v[92:95]
	v_mfma_f32_16x16x32_bf16 v[88:91], v[160:163], v[196:199], v[88:91]
	v_mfma_f32_16x16x32_bf16 v[76:79], v[146:149], v[204:207], v[76:79]
	v_mfma_f32_16x16x32_bf16 v[72:75], v[160:163], v[204:207], v[72:75]
	s_barrier
	s_setprio 0
	s_add_i32 s42, 0, 0x1c000
	s_add_i32 s0, s17, s45
	v_add_u32_e32 v183, s42, v143
	v_lshl_add_u64 v[224:225], v[224:225], 0, s[8:9]
	s_mov_b32 m0, s0
	ds_read_b128 v[208:211], v183
	ds_read_b128 v[212:215], v183 offset:1024
	ds_read_b128 v[216:219], v183 offset:2048
	ds_read_b128 v[220:223], v183 offset:3072
	global_load_lds_dwordx4 v[224:225], off
	v_lshl_add_u64 v[224:225], v[226:227], 0, s[8:9]
	s_add_i32 m0, s0, 0x2000
	s_nop 0
	global_load_lds_dwordx4 v[224:225], off
	s_setprio 1
	s_barrier
	s_waitcnt lgkmcnt(0)
	v_mfma_f32_16x16x32_bf16 v[116:119], v[208:211], v[164:167], v[116:119]
	v_mfma_f32_16x16x32_bf16 v[112:115], v[216:219], v[164:167], v[112:115]
	v_mfma_f32_16x16x32_bf16 v[100:103], v[208:211], v[184:187], v[100:103]
	v_mfma_f32_16x16x32_bf16 v[96:99], v[216:219], v[184:187], v[96:99]
	v_mfma_f32_16x16x32_bf16 v[84:87], v[208:211], v[192:195], v[84:87]
	v_mfma_f32_16x16x32_bf16 v[80:83], v[216:219], v[192:195], v[80:83]
	s_mov_b32 m0, s6
	v_mfma_f32_16x16x32_bf16 v[68:71], v[208:211], v[200:203], v[68:71]
	v_lshl_add_u64 v[224:225], v[228:229], 0, s[8:9]
	v_mfma_f32_16x16x32_bf16 v[64:67], v[216:219], v[200:203], v[64:67]
	v_mfma_f32_16x16x32_bf16 v[116:119], v[212:215], v[168:171], v[116:119]
	v_mfma_f32_16x16x32_bf16 v[112:115], v[220:223], v[168:171], v[112:115]
	v_mfma_f32_16x16x32_bf16 v[100:103], v[212:215], v[188:191], v[100:103]
	v_mfma_f32_16x16x32_bf16 v[96:99], v[220:223], v[188:191], v[96:99]
	v_mfma_f32_16x16x32_bf16 v[84:87], v[212:215], v[196:199], v[84:87]
	v_mfma_f32_16x16x32_bf16 v[80:83], v[220:223], v[196:199], v[80:83]
	v_mfma_f32_16x16x32_bf16 v[68:71], v[212:215], v[204:207], v[68:71]
	v_mfma_f32_16x16x32_bf16 v[64:67], v[220:223], v[204:207], v[64:67]
	s_barrier
	s_setprio 0
	ds_read_b128 v[164:167], v145 offset:49152
	ds_read_b128 v[168:171], v145 offset:50176
	ds_read_b128 v[184:187], v145 offset:51200
	ds_read_b128 v[188:191], v145 offset:52224
	ds_read_b128 v[192:195], v145 offset:53248
	ds_read_b128 v[196:199], v145 offset:54272
	ds_read_b128 v[200:203], v145 offset:55296
	ds_read_b128 v[204:207], v145 offset:56320
	global_load_lds_dwordx4 v[224:225], off
	v_lshl_add_u64 v[224:225], v[230:231], 0, s[8:9]
	s_mov_b32 m0, s50
	s_nop 0
	global_load_lds_dwordx4 v[224:225], off
	s_setprio 1
	s_barrier
	s_waitcnt lgkmcnt(0)
	v_mfma_f32_16x16x32_bf16 v[60:63], v[138:141], v[164:167], v[60:63]
	v_mfma_f32_16x16x32_bf16 v[56:59], v[150:153], v[164:167], v[56:59]
	v_mfma_f32_16x16x32_bf16 v[44:47], v[138:141], v[184:187], v[44:47]
	v_mfma_f32_16x16x32_bf16 v[40:43], v[150:153], v[184:187], v[40:43]
	v_mfma_f32_16x16x32_bf16 v[28:31], v[138:141], v[192:195], v[28:31]
	v_mfma_f32_16x16x32_bf16 v[24:27], v[150:153], v[192:195], v[24:27]
	v_mfma_f32_16x16x32_bf16 v[12:15], v[138:141], v[200:203], v[12:15]
	v_mfma_f32_16x16x32_bf16 v[8:11], v[150:153], v[200:203], v[8:11]
	v_mfma_f32_16x16x32_bf16 v[60:63], v[146:149], v[168:171], v[60:63]
	v_mfma_f32_16x16x32_bf16 v[56:59], v[160:163], v[168:171], v[56:59]
	v_mfma_f32_16x16x32_bf16 v[44:47], v[146:149], v[188:191], v[44:47]
	v_mfma_f32_16x16x32_bf16 v[40:43], v[160:163], v[188:191], v[40:43]
	v_mfma_f32_16x16x32_bf16 v[28:31], v[146:149], v[196:199], v[28:31]
	v_mfma_f32_16x16x32_bf16 v[24:27], v[160:163], v[196:199], v[24:27]
	v_mfma_f32_16x16x32_bf16 v[12:15], v[146:149], v[204:207], v[12:15]
	v_mfma_f32_16x16x32_bf16 v[8:11], v[160:163], v[204:207], v[8:11]
	s_barrier
	s_setprio 0
	s_add_u32 s0, s34, 0x40080
	s_addc_u32 s1, s35, 0
	s_add_i32 s17, s42, s45
	v_lshl_add_u64 v[138:139], s[0:1], 0, v[154:155]
	s_mov_b32 m0, s17
	s_nop 0
	global_load_lds_dwordx4 v[138:139], off
	v_lshl_add_u64 v[138:139], s[0:1], 0, v[128:129]
	s_add_i32 m0, s17, 0x2000
	s_nop 0
	global_load_lds_dwordx4 v[138:139], off
	s_waitcnt vmcnt(6)
	s_setprio 1
	s_barrier
	v_mfma_f32_16x16x32_bf16 v[52:55], v[208:211], v[164:167], v[52:55]
	v_mfma_f32_16x16x32_bf16 v[48:51], v[216:219], v[164:167], v[48:51]
	v_mfma_f32_16x16x32_bf16 v[36:39], v[208:211], v[184:187], v[36:39]
	v_mfma_f32_16x16x32_bf16 v[32:35], v[216:219], v[184:187], v[32:35]
	v_mfma_f32_16x16x32_bf16 v[20:23], v[208:211], v[192:195], v[20:23]
	v_mfma_f32_16x16x32_bf16 v[16:19], v[216:219], v[192:195], v[16:19]
	s_add_i32 s61, s61, 2
	v_mfma_f32_16x16x32_bf16 v[4:7], v[208:211], v[200:203], v[4:7]
	s_add_u32 s40, s40, 0x100
	v_mfma_f32_16x16x32_bf16 v[0:3], v[216:219], v[200:203], v[0:3]
	s_addc_u32 s41, s41, 0
	v_mfma_f32_16x16x32_bf16 v[52:55], v[212:215], v[168:171], v[52:55]
	s_add_u32 s58, s58, 0x100
	v_mfma_f32_16x16x32_bf16 v[48:51], v[220:223], v[168:171], v[48:51]
	s_addc_u32 s60, s60, 0
	v_mfma_f32_16x16x32_bf16 v[36:39], v[212:215], v[188:191], v[36:39]
	s_cmp_gt_u32 s61, 13
	v_mfma_f32_16x16x32_bf16 v[32:35], v[220:223], v[188:191], v[32:35]
	v_mfma_f32_16x16x32_bf16 v[20:23], v[212:215], v[196:199], v[20:23]
	v_mfma_f32_16x16x32_bf16 v[16:19], v[220:223], v[196:199], v[16:19]
	v_mfma_f32_16x16x32_bf16 v[4:7], v[212:215], v[204:207], v[4:7]
	v_mfma_f32_16x16x32_bf16 v[0:3], v[220:223], v[204:207], v[0:3]
	s_barrier
	s_setprio 0
	s_cbranch_scc0 .LBB0_115
